# prologue: once-read f32 inputs (x, layer-0 weights) loaded with the non-temporal policy as well
# speedup vs baseline: 1.0368x; 1.0187x over previous
.LBB0_32:
	s_cmpk_gt_i32 s22, 0xfff
	s_mov_b64 s[18:19], -1
	s_cbranch_scc0 .LBB0_46
	s_cmpk_gt_u32 s22, 0x1fff
	s_cbranch_scc0 .LBB0_43
	s_cmpk_gt_u32 s22, 0x27ff
	s_cbranch_scc0 .LBB0_40
	s_cmpk_gt_u32 s22, 0x37ff
	s_cbranch_scc0 .LBB0_37
	s_load_dwordx2 s[48:49], s[20:21], 0x60
	s_lshl_b32 s18, s22, 6
	s_lshl_b32 s4, s22, 1
	s_and_b32 s18, s18, 0x7c0
	s_and_b32 s4, s4, 0x7c0
	s_lshl_b32 s19, s18, 2
	s_waitcnt lgkmcnt(0)
	s_add_u32 s48, s48, s19
	v_or_b32_e32 v2, s4, v76
	s_addc_u32 s49, s49, 0
	v_lshl_add_u64 v[0:1], s[48:49], 0, v[66:67]
	v_lshlrev_b32_e32 v2, 13, v2
	v_mov_b32_e32 v3, v67
	v_lshl_add_u64 v[60:61], v[0:1], 0, v[2:3]
	v_add_co_u32_e32 v4, vcc, s27, v60
	s_lshl_b32 s4, s4, 1
	s_nop 0
	v_addc_co_u32_e32 v5, vcc, 0, v61, vcc
	v_add_co_u32_e32 v8, vcc, s28, v60
	global_load_dwordx4 v[0:3], v[60:61], off nt
	s_nop 0
	global_load_dwordx4 v[4:7], v[4:5], off nt
	v_addc_co_u32_e32 v9, vcc, 0, v61, vcc
	v_add_co_u32_e32 v12, vcc, s29, v60
	s_nop 1
	v_addc_co_u32_e32 v13, vcc, 0, v61, vcc
	v_add_co_u32_e32 v16, vcc, s30, v60
	global_load_dwordx4 v[8:11], v[8:9], off nt
	s_nop 0
	global_load_dwordx4 v[12:15], v[12:13], off nt
	v_addc_co_u32_e32 v17, vcc, 0, v61, vcc
	v_add_co_u32_e32 v20, vcc, s31, v60
	s_nop 1
	v_addc_co_u32_e32 v21, vcc, 0, v61, vcc
	v_add_co_u32_e32 v24, vcc, s34, v60
	global_load_dwordx4 v[16:19], v[16:17], off nt
	s_nop 0
	global_load_dwordx4 v[20:23], v[20:21], off nt
	v_addc_co_u32_e32 v25, vcc, 0, v61, vcc
	v_add_co_u32_e32 v28, vcc, s35, v60
	s_nop 1
	v_addc_co_u32_e32 v29, vcc, 0, v61, vcc
	v_add_co_u32_e32 v32, vcc, s36, v60
	global_load_dwordx4 v[24:27], v[24:25], off nt
	s_nop 0
	global_load_dwordx4 v[28:31], v[28:29], off nt
	v_addc_co_u32_e32 v33, vcc, 0, v61, vcc
	v_add_co_u32_e32 v36, vcc, s37, v60
	s_nop 1
	v_addc_co_u32_e32 v37, vcc, 0, v61, vcc
	v_add_co_u32_e32 v40, vcc, s38, v60
	global_load_dwordx4 v[32:35], v[32:33], off nt
	s_nop 0
	global_load_dwordx4 v[36:39], v[36:37], off nt
	v_addc_co_u32_e32 v41, vcc, 0, v61, vcc
	v_add_co_u32_e32 v44, vcc, s39, v60
	s_nop 1
	v_addc_co_u32_e32 v45, vcc, 0, v61, vcc
	v_add_co_u32_e32 v48, vcc, s40, v60
	global_load_dwordx4 v[40:43], v[40:41], off nt
	s_nop 0
	global_load_dwordx4 v[44:47], v[44:45], off nt
	v_addc_co_u32_e32 v49, vcc, 0, v61, vcc
	v_add_co_u32_e32 v52, vcc, s41, v60
	s_nop 1
	v_addc_co_u32_e32 v53, vcc, 0, v61, vcc
	global_load_dwordx4 v[48:51], v[48:49], off nt
	s_nop 0
	global_load_dwordx4 v[52:55], v[52:53], off nt
	v_add_co_u32_e32 v56, vcc, s42, v60
	s_nop 1
	v_addc_co_u32_e32 v57, vcc, 0, v61, vcc
	global_load_dwordx4 v[56:59], v[56:57], off nt
	v_add_co_u32_e32 v60, vcc, s43, v60
	s_nop 1
	v_addc_co_u32_e32 v61, vcc, 0, v61, vcc
	global_load_dwordx4 v[60:63], v[60:61], off nt
	s_waitcnt vmcnt(15)
	ds_write2_b32 v77, v0, v1 offset1:1
	ds_write2_b32 v77, v2, v3 offset0:2 offset1:3
	s_waitcnt vmcnt(14)
	ds_write2_b32 v87, v4, v5 offset1:1
	ds_write2_b32 v88, v6, v7 offset1:1
	s_waitcnt vmcnt(13)
	ds_write2_b32 v89, v8, v9 offset1:1
	ds_write2_b32 v90, v10, v11 offset1:1
	s_waitcnt vmcnt(12)
	ds_write2_b32 v91, v12, v13 offset1:1
	ds_write2_b32 v92, v14, v15 offset1:1
	s_waitcnt vmcnt(11)
	ds_write2_b32 v93, v16, v17 offset1:1
	ds_write2_b32 v94, v18, v19 offset1:1
	s_waitcnt vmcnt(10)
	ds_write2_b32 v95, v20, v21 offset1:1
	ds_write2_b32 v96, v22, v23 offset1:1
	s_waitcnt vmcnt(9)
	ds_write2_b32 v97, v24, v25 offset1:1
	ds_write2_b32 v98, v26, v27 offset1:1
	s_waitcnt vmcnt(8)
	ds_write2_b32 v99, v28, v29 offset1:1
	ds_write2_b32 v100, v30, v31 offset1:1
	s_waitcnt vmcnt(7)
	ds_write2_b32 v101, v32, v33 offset1:1
	ds_write2_b32 v102, v34, v35 offset1:1
	s_waitcnt vmcnt(6)
	ds_write2_b32 v103, v36, v37 offset1:1
	ds_write2_b32 v104, v38, v39 offset1:1
	s_waitcnt vmcnt(5)
	ds_write2_b32 v105, v40, v41 offset1:1
	ds_write2_b32 v106, v42, v43 offset1:1
	s_waitcnt vmcnt(4)
	ds_write2_b32 v107, v44, v45 offset1:1
	ds_write2_b32 v108, v46, v47 offset1:1
	s_waitcnt vmcnt(3)
	ds_write2_b32 v109, v48, v49 offset1:1
	ds_write2_b32 v110, v50, v51 offset1:1
	s_waitcnt vmcnt(2)
	ds_write2_b32 v111, v52, v53 offset1:1
	ds_write2_b32 v112, v54, v55 offset1:1
	s_waitcnt vmcnt(1)
	ds_write2_b32 v113, v56, v57 offset1:1
	ds_write2_b32 v114, v58, v59 offset1:1
	s_waitcnt vmcnt(0)
	ds_write2_b32 v115, v60, v61 offset1:1
	ds_write2_b32 v116, v62, v63 offset1:1
	s_waitcnt lgkmcnt(0)
	ds_read2_b32 v[6:7], v79 offset1:8
	ds_read2_b32 v[8:9], v79 offset0:65 offset1:73
	ds_read2_b32 v[10:11], v79 offset0:130 offset1:138
	ds_read2_b32 v[12:13], v79 offset0:195 offset1:203
	ds_read2_b32 v[14:15], v117 offset0:4 offset1:12
	s_waitcnt lgkmcnt(4)
	v_bfe_u32 v2, v6, 16, 1
	v_add3_u32 v2, v6, v2, s44
	s_waitcnt lgkmcnt(3)
	v_bfe_u32 v3, v8, 16, 1
	v_lshrrev_b32_e32 v2, 16, v2
	v_add3_u32 v3, v8, v3, s44
	ds_read2_b32 v[16:17], v117 offset0:69 offset1:77
	v_and_or_b32 v2, v3, s45, v2
	s_waitcnt lgkmcnt(3)
	v_bfe_u32 v3, v10, 16, 1
	v_add3_u32 v3, v10, v3, s44
	s_waitcnt lgkmcnt(2)
	v_bfe_u32 v4, v12, 16, 1
	ds_read2_b32 v[18:19], v117 offset0:134 offset1:142
	v_lshrrev_b32_e32 v3, 16, v3
	v_add3_u32 v4, v12, v4, s44
	ds_read2_b32 v[20:21], v117 offset0:199 offset1:207
	v_and_or_b32 v3, v4, s45, v3
	s_waitcnt lgkmcnt(3)
	v_bfe_u32 v4, v14, 16, 1
	v_add3_u32 v4, v14, v4, s44
	s_waitcnt lgkmcnt(2)
	v_bfe_u32 v5, v16, 16, 1
	v_lshrrev_b32_e32 v4, 16, v4
	v_add3_u32 v5, v16, v5, s44
	v_and_or_b32 v4, v5, s45, v4
	s_waitcnt lgkmcnt(1)
	v_bfe_u32 v5, v18, 16, 1
	v_add3_u32 v5, v18, v5, s44
	s_waitcnt lgkmcnt(0)
	v_bfe_u32 v6, v20, 16, 1
	v_lshrrev_b32_e32 v5, 16, v5
	v_add3_u32 v6, v20, v6, s44
	v_and_or_b32 v5, v6, s45, v5
	v_or_b32_e32 v6, s18, v78
	v_lshl_add_u64 v[0:1], v[74:75], 0, s[4:5]
	v_lshlrev_b32_e32 v22, 12, v6
	v_mov_b32_e32 v23, v67
	v_lshl_add_u64 v[22:23], v[0:1], 0, v[22:23]
	global_store_dwordx4 v[22:23], v[2:5], off
	v_bfe_u32 v6, v21, 16, 1
	v_add3_u32 v6, v21, v6, s44
	v_bfe_u32 v2, v7, 16, 1
	v_add3_u32 v2, v7, v2, s44
	v_bfe_u32 v3, v9, 16, 1
	v_lshrrev_b32_e32 v2, 16, v2
	v_add3_u32 v3, v9, v3, s44
	v_and_or_b32 v2, v3, s45, v2
	v_bfe_u32 v3, v11, 16, 1
	v_add3_u32 v3, v11, v3, s44
	v_bfe_u32 v4, v13, 16, 1
	v_lshrrev_b32_e32 v3, 16, v3
	v_add3_u32 v4, v13, v4, s44
	v_and_or_b32 v3, v4, s45, v3
	v_bfe_u32 v4, v15, 16, 1
	v_add3_u32 v4, v15, v4, s44
	v_bfe_u32 v5, v17, 16, 1
	v_lshrrev_b32_e32 v4, 16, v4
	v_add3_u32 v5, v17, v5, s44
	v_and_or_b32 v4, v5, s45, v4
	v_bfe_u32 v5, v19, 16, 1
	v_add3_u32 v5, v19, v5, s44
	v_lshrrev_b32_e32 v5, 16, v5
	v_and_or_b32 v5, v6, s45, v5
	v_or_b32_e32 v6, s18, v80
	v_lshlrev_b32_e32 v6, 12, v6
	v_mov_b32_e32 v7, v67
	ds_read2_b32 v[8:9], v79 offset0:16 offset1:24
	v_lshl_add_u64 v[6:7], v[0:1], 0, v[6:7]
	global_store_dwordx4 v[6:7], v[2:5], off
	ds_read2_b32 v[6:7], v79 offset0:81 offset1:89
	ds_read2_b32 v[10:11], v79 offset0:146 offset1:154
	ds_read2_b32 v[12:13], v79 offset0:211 offset1:219
	s_waitcnt lgkmcnt(3)
	v_bfe_u32 v2, v8, 16, 1
	v_add3_u32 v2, v8, v2, s44
	s_waitcnt lgkmcnt(2)
	v_bfe_u32 v3, v6, 16, 1
	ds_read2_b32 v[14:15], v117 offset0:20 offset1:28
	v_lshrrev_b32_e32 v2, 16, v2
	v_add3_u32 v3, v6, v3, s44
	ds_read2_b32 v[16:17], v117 offset0:85 offset1:93
	v_and_or_b32 v2, v3, s45, v2
	s_waitcnt lgkmcnt(3)
	v_bfe_u32 v3, v10, 16, 1
	v_add3_u32 v3, v10, v3, s44
	s_waitcnt lgkmcnt(2)
	v_bfe_u32 v4, v12, 16, 1
	ds_read2_b32 v[18:19], v117 offset0:150 offset1:158
	v_lshrrev_b32_e32 v3, 16, v3
	v_add3_u32 v4, v12, v4, s44
	ds_read2_b32 v[20:21], v117 offset0:215 offset1:223
	v_and_or_b32 v3, v4, s45, v3
	s_waitcnt lgkmcnt(3)
	v_bfe_u32 v4, v14, 16, 1
	v_add3_u32 v4, v14, v4, s44
	s_waitcnt lgkmcnt(2)
	v_bfe_u32 v5, v16, 16, 1
	v_lshrrev_b32_e32 v4, 16, v4
	v_add3_u32 v5, v16, v5, s44
	v_and_or_b32 v4, v5, s45, v4
	s_waitcnt lgkmcnt(1)
	v_bfe_u32 v5, v18, 16, 1
	v_add3_u32 v5, v18, v5, s44
	s_waitcnt lgkmcnt(0)
	v_bfe_u32 v6, v20, 16, 1
	v_lshrrev_b32_e32 v5, 16, v5
	v_add3_u32 v6, v20, v6, s44
	v_and_or_b32 v5, v6, s45, v5
	v_or_b32_e32 v6, s18, v81
	v_lshlrev_b32_e32 v22, 12, v6
	v_mov_b32_e32 v23, v67
	v_lshl_add_u64 v[22:23], v[0:1], 0, v[22:23]
	global_store_dwordx4 v[22:23], v[2:5], off
	v_bfe_u32 v6, v21, 16, 1
	v_add3_u32 v6, v21, v6, s44
	v_bfe_u32 v2, v9, 16, 1
	v_add3_u32 v2, v9, v2, s44
	v_bfe_u32 v3, v7, 16, 1
	v_lshrrev_b32_e32 v2, 16, v2
	v_add3_u32 v3, v7, v3, s44
	v_and_or_b32 v2, v3, s45, v2
	v_bfe_u32 v3, v11, 16, 1
	v_add3_u32 v3, v11, v3, s44
	v_bfe_u32 v4, v13, 16, 1
	v_lshrrev_b32_e32 v3, 16, v3
	v_add3_u32 v4, v13, v4, s44
	v_and_or_b32 v3, v4, s45, v3
	v_bfe_u32 v4, v15, 16, 1
	v_add3_u32 v4, v15, v4, s44
	v_bfe_u32 v5, v17, 16, 1
	v_lshrrev_b32_e32 v4, 16, v4
	v_add3_u32 v5, v17, v5, s44
	v_and_or_b32 v4, v5, s45, v4
	v_bfe_u32 v5, v19, 16, 1
	v_add3_u32 v5, v19, v5, s44
	v_lshrrev_b32_e32 v5, 16, v5
	v_and_or_b32 v5, v6, s45, v5
	v_or_b32_e32 v6, s18, v82
	v_lshlrev_b32_e32 v6, 12, v6
	v_mov_b32_e32 v7, v67
	ds_read2_b32 v[8:9], v79 offset0:32 offset1:40
	v_lshl_add_u64 v[6:7], v[0:1], 0, v[6:7]
	global_store_dwordx4 v[6:7], v[2:5], off
	ds_read2_b32 v[6:7], v79 offset0:97 offset1:105
	ds_read2_b32 v[10:11], v79 offset0:162 offset1:170
	ds_read2_b32 v[12:13], v79 offset0:227 offset1:235
	s_waitcnt lgkmcnt(3)
	v_bfe_u32 v2, v8, 16, 1
	v_add3_u32 v2, v8, v2, s44
	s_waitcnt lgkmcnt(2)
	v_bfe_u32 v3, v6, 16, 1
	ds_read2_b32 v[14:15], v117 offset0:36 offset1:44
	v_lshrrev_b32_e32 v2, 16, v2
	v_add3_u32 v3, v6, v3, s44
	ds_read2_b32 v[16:17], v117 offset0:101 offset1:109
	v_and_or_b32 v2, v3, s45, v2
	s_waitcnt lgkmcnt(3)
	v_bfe_u32 v3, v10, 16, 1
	v_add3_u32 v3, v10, v3, s44
	s_waitcnt lgkmcnt(2)
	v_bfe_u32 v4, v12, 16, 1
	ds_read2_b32 v[18:19], v117 offset0:166 offset1:174
	v_lshrrev_b32_e32 v3, 16, v3
	v_add3_u32 v4, v12, v4, s44
	ds_read2_b32 v[20:21], v117 offset0:231 offset1:239
	v_and_or_b32 v3, v4, s45, v3
	s_waitcnt lgkmcnt(3)
	v_bfe_u32 v4, v14, 16, 1
	v_add3_u32 v4, v14, v4, s44
	s_waitcnt lgkmcnt(2)
	v_bfe_u32 v5, v16, 16, 1
	v_lshrrev_b32_e32 v4, 16, v4
	v_add3_u32 v5, v16, v5, s44
	v_and_or_b32 v4, v5, s45, v4
	s_waitcnt lgkmcnt(1)
	v_bfe_u32 v5, v18, 16, 1
	v_add3_u32 v5, v18, v5, s44
	s_waitcnt lgkmcnt(0)
	v_bfe_u32 v6, v20, 16, 1
	v_lshrrev_b32_e32 v5, 16, v5
	v_add3_u32 v6, v20, v6, s44
	v_and_or_b32 v5, v6, s45, v5
	v_or_b32_e32 v6, s18, v83
	v_lshlrev_b32_e32 v22, 12, v6
	v_mov_b32_e32 v23, v67
	v_lshl_add_u64 v[22:23], v[0:1], 0, v[22:23]
	global_store_dwordx4 v[22:23], v[2:5], off
	v_bfe_u32 v6, v21, 16, 1
	v_add3_u32 v6, v21, v6, s44
	v_bfe_u32 v2, v9, 16, 1
	v_add3_u32 v2, v9, v2, s44
	v_bfe_u32 v3, v7, 16, 1
	v_lshrrev_b32_e32 v2, 16, v2
	v_add3_u32 v3, v7, v3, s44
	v_and_or_b32 v2, v3, s45, v2
	v_bfe_u32 v3, v11, 16, 1
	v_add3_u32 v3, v11, v3, s44
	v_bfe_u32 v4, v13, 16, 1
	v_lshrrev_b32_e32 v3, 16, v3
	v_add3_u32 v4, v13, v4, s44
	v_and_or_b32 v3, v4, s45, v3
	v_bfe_u32 v4, v15, 16, 1
	v_add3_u32 v4, v15, v4, s44
	v_bfe_u32 v5, v17, 16, 1
	v_lshrrev_b32_e32 v4, 16, v4
	v_add3_u32 v5, v17, v5, s44
	v_and_or_b32 v4, v5, s45, v4
	v_bfe_u32 v5, v19, 16, 1
	v_add3_u32 v5, v19, v5, s44
	v_lshrrev_b32_e32 v5, 16, v5
	v_and_or_b32 v5, v6, s45, v5
	v_or_b32_e32 v6, s18, v84
	v_lshlrev_b32_e32 v6, 12, v6
	v_mov_b32_e32 v7, v67
	ds_read2_b32 v[8:9], v79 offset0:48 offset1:56
	v_lshl_add_u64 v[6:7], v[0:1], 0, v[6:7]
	global_store_dwordx4 v[6:7], v[2:5], off
	ds_read2_b32 v[6:7], v79 offset0:113 offset1:121
	ds_read2_b32 v[10:11], v79 offset0:178 offset1:186
	ds_read2_b32 v[12:13], v79 offset0:243 offset1:251
	s_waitcnt lgkmcnt(3)
	v_bfe_u32 v2, v8, 16, 1
	v_add3_u32 v2, v8, v2, s44
	s_waitcnt lgkmcnt(2)
	v_bfe_u32 v3, v6, 16, 1
	ds_read2_b32 v[14:15], v117 offset0:52 offset1:60
	v_lshrrev_b32_e32 v2, 16, v2
	v_add3_u32 v3, v6, v3, s44
	ds_read2_b32 v[16:17], v117 offset0:117 offset1:125
	v_and_or_b32 v2, v3, s45, v2
	s_waitcnt lgkmcnt(3)
	v_bfe_u32 v3, v10, 16, 1
	v_add3_u32 v3, v10, v3, s44
	s_waitcnt lgkmcnt(2)
	v_bfe_u32 v4, v12, 16, 1
	ds_read2_b32 v[18:19], v117 offset0:182 offset1:190
	v_lshrrev_b32_e32 v3, 16, v3
	v_add3_u32 v4, v12, v4, s44
	ds_read2_b32 v[20:21], v117 offset0:247 offset1:255
	v_and_or_b32 v3, v4, s45, v3
	s_waitcnt lgkmcnt(3)
	v_bfe_u32 v4, v14, 16, 1
	v_add3_u32 v4, v14, v4, s44
	s_waitcnt lgkmcnt(2)
	v_bfe_u32 v5, v16, 16, 1
	v_lshrrev_b32_e32 v4, 16, v4
	v_add3_u32 v5, v16, v5, s44
	v_and_or_b32 v4, v5, s45, v4
	s_waitcnt lgkmcnt(1)
	v_bfe_u32 v5, v18, 16, 1
	v_add3_u32 v5, v18, v5, s44
	s_waitcnt lgkmcnt(0)
	v_bfe_u32 v6, v20, 16, 1
	v_lshrrev_b32_e32 v5, 16, v5
	v_add3_u32 v6, v20, v6, s44
	v_and_or_b32 v5, v6, s45, v5
	v_or_b32_e32 v6, s18, v85
	v_lshlrev_b32_e32 v22, 12, v6
	v_mov_b32_e32 v23, v67
	v_lshl_add_u64 v[22:23], v[0:1], 0, v[22:23]
	global_store_dwordx4 v[22:23], v[2:5], off
	v_bfe_u32 v6, v21, 16, 1
	v_add3_u32 v6, v21, v6, s44
	v_bfe_u32 v2, v9, 16, 1
	v_add3_u32 v2, v9, v2, s44
	v_bfe_u32 v3, v7, 16, 1
	v_lshrrev_b32_e32 v2, 16, v2
	v_add3_u32 v3, v7, v3, s44
	v_and_or_b32 v2, v3, s45, v2
	v_bfe_u32 v3, v11, 16, 1
	v_add3_u32 v3, v11, v3, s44
	v_bfe_u32 v4, v13, 16, 1
	v_lshrrev_b32_e32 v3, 16, v3
	v_add3_u32 v4, v13, v4, s44
	v_and_or_b32 v3, v4, s45, v3
	v_bfe_u32 v4, v15, 16, 1
	v_add3_u32 v4, v15, v4, s44
	v_bfe_u32 v5, v17, 16, 1
	v_lshrrev_b32_e32 v4, 16, v4
	v_add3_u32 v5, v17, v5, s44
	v_and_or_b32 v4, v5, s45, v4
	v_bfe_u32 v5, v19, 16, 1
	v_add3_u32 v5, v19, v5, s44
	v_lshrrev_b32_e32 v5, 16, v5
	v_and_or_b32 v5, v6, s45, v5
	v_or_b32_e32 v6, s18, v86
	v_lshlrev_b32_e32 v6, 12, v6
	v_mov_b32_e32 v7, v67
	v_lshl_add_u64 v[0:1], v[0:1], 0, v[6:7]
	global_store_dwordx4 v[0:1], v[2:5], off
	s_waitcnt lgkmcnt(0)
	s_mov_b64 s[18:19], 0
.LBB0_37:
	s_andn2_b64 vcc, exec, s[18:19]
	s_cbranch_vccnz .LBB0_39
	s_load_dwordx2 s[18:19], s[20:21], 0x10
	s_add_i32 s4, s22, 0xffffd800
	s_lshr_b32 s4, s4, 10
	s_lshl_b64 s[48:49], s[4:5], 24
	v_mov_b32_e32 v3, v67
	s_waitcnt lgkmcnt(0)
	s_add_u32 s23, s18, s48
	s_addc_u32 s47, s19, s49
	s_lshl_b64 s[18:19], s[4:5], 23
	s_add_u32 s48, s1, s18
	s_addc_u32 s49, s3, s19
	s_lshl_b32 s4, s22, 1
	s_and_b32 s50, s4, 0x7c0
	s_lshl_b32 s4, s22, 6
	s_and_b32 s4, s4, 0x7c0
	s_lshl_b32 s18, s4, 2
	s_add_u32 s18, s23, s18
	v_or_b32_e32 v2, s50, v76
	s_addc_u32 s19, s47, 0
	v_lshl_add_u64 v[0:1], s[18:19], 0, v[66:67]
	v_lshlrev_b32_e32 v2, 13, v2
	v_lshl_add_u64 v[60:61], v[0:1], 0, v[2:3]
	v_add_co_u32_e32 v4, vcc, s27, v60
	s_lshl_b32 s18, s50, 1
	s_nop 0
	v_addc_co_u32_e32 v5, vcc, 0, v61, vcc
	v_add_co_u32_e32 v8, vcc, s28, v60
	global_load_dwordx4 v[0:3], v[60:61], off nt
	s_nop 0
	global_load_dwordx4 v[4:7], v[4:5], off nt
	v_addc_co_u32_e32 v9, vcc, 0, v61, vcc
	v_add_co_u32_e32 v12, vcc, s29, v60
	s_add_u32 s18, s48, s18
	s_nop 0
	v_addc_co_u32_e32 v13, vcc, 0, v61, vcc
	v_add_co_u32_e32 v16, vcc, s30, v60
	global_load_dwordx4 v[8:11], v[8:9], off nt
	s_nop 0
	global_load_dwordx4 v[12:15], v[12:13], off nt
	v_addc_co_u32_e32 v17, vcc, 0, v61, vcc
	v_add_co_u32_e32 v20, vcc, s31, v60
	s_addc_u32 s19, s49, 0
	s_nop 0
	v_addc_co_u32_e32 v21, vcc, 0, v61, vcc
	v_add_co_u32_e32 v24, vcc, s34, v60
	global_load_dwordx4 v[16:19], v[16:17], off nt
	s_nop 0
	global_load_dwordx4 v[20:23], v[20:21], off nt
	v_addc_co_u32_e32 v25, vcc, 0, v61, vcc
	v_add_co_u32_e32 v28, vcc, s35, v60
	s_nop 1
	v_addc_co_u32_e32 v29, vcc, 0, v61, vcc
	v_add_co_u32_e32 v32, vcc, s36, v60
	global_load_dwordx4 v[24:27], v[24:25], off nt
	s_nop 0
	global_load_dwordx4 v[28:31], v[28:29], off nt
	v_addc_co_u32_e32 v33, vcc, 0, v61, vcc
	v_add_co_u32_e32 v36, vcc, s37, v60
	s_nop 1
	v_addc_co_u32_e32 v37, vcc, 0, v61, vcc
	v_add_co_u32_e32 v40, vcc, s38, v60
	global_load_dwordx4 v[32:35], v[32:33], off nt
	s_nop 0
	global_load_dwordx4 v[36:39], v[36:37], off nt
	v_addc_co_u32_e32 v41, vcc, 0, v61, vcc
	v_add_co_u32_e32 v44, vcc, s39, v60
	s_nop 1
	v_addc_co_u32_e32 v45, vcc, 0, v61, vcc
	v_add_co_u32_e32 v48, vcc, s40, v60
	global_load_dwordx4 v[40:43], v[40:41], off nt
	s_nop 0
	global_load_dwordx4 v[44:47], v[44:45], off nt
	v_addc_co_u32_e32 v49, vcc, 0, v61, vcc
	v_add_co_u32_e32 v52, vcc, s41, v60
	s_nop 1
	v_addc_co_u32_e32 v53, vcc, 0, v61, vcc
	global_load_dwordx4 v[48:51], v[48:49], off nt
	s_nop 0
	global_load_dwordx4 v[52:55], v[52:53], off nt
	v_add_co_u32_e32 v56, vcc, s42, v60
	s_nop 1
	v_addc_co_u32_e32 v57, vcc, 0, v61, vcc
	global_load_dwordx4 v[56:59], v[56:57], off nt
	v_add_co_u32_e32 v60, vcc, s43, v60
	s_nop 1
	v_addc_co_u32_e32 v61, vcc, 0, v61, vcc
	global_load_dwordx4 v[60:63], v[60:61], off nt
	s_waitcnt vmcnt(15)
	ds_write2_b32 v77, v0, v1 offset1:1
	ds_write2_b32 v77, v2, v3 offset0:2 offset1:3
	s_waitcnt vmcnt(14)
	ds_write2_b32 v87, v4, v5 offset1:1
	ds_write2_b32 v88, v6, v7 offset1:1
	s_waitcnt vmcnt(13)
	ds_write2_b32 v89, v8, v9 offset1:1
	ds_write2_b32 v90, v10, v11 offset1:1
	s_waitcnt vmcnt(12)
	ds_write2_b32 v91, v12, v13 offset1:1
	ds_write2_b32 v92, v14, v15 offset1:1
	s_waitcnt vmcnt(11)
	ds_write2_b32 v93, v16, v17 offset1:1
	ds_write2_b32 v94, v18, v19 offset1:1
	s_waitcnt vmcnt(10)
	ds_write2_b32 v95, v20, v21 offset1:1
	ds_write2_b32 v96, v22, v23 offset1:1
	s_waitcnt vmcnt(9)
	ds_write2_b32 v97, v24, v25 offset1:1
	ds_write2_b32 v98, v26, v27 offset1:1
	s_waitcnt vmcnt(8)
	ds_write2_b32 v99, v28, v29 offset1:1
	ds_write2_b32 v100, v30, v31 offset1:1
	s_waitcnt vmcnt(7)
	ds_write2_b32 v101, v32, v33 offset1:1
	ds_write2_b32 v102, v34, v35 offset1:1
	s_waitcnt vmcnt(6)
	ds_write2_b32 v103, v36, v37 offset1:1
	ds_write2_b32 v104, v38, v39 offset1:1
	s_waitcnt vmcnt(5)
	ds_write2_b32 v105, v40, v41 offset1:1
	ds_write2_b32 v106, v42, v43 offset1:1
	s_waitcnt vmcnt(4)
	ds_write2_b32 v107, v44, v45 offset1:1
	ds_write2_b32 v108, v46, v47 offset1:1
	s_waitcnt vmcnt(3)
	ds_write2_b32 v109, v48, v49 offset1:1
	ds_write2_b32 v110, v50, v51 offset1:1
	s_waitcnt vmcnt(2)
	ds_write2_b32 v111, v52, v53 offset1:1
	ds_write2_b32 v112, v54, v55 offset1:1
	s_waitcnt vmcnt(1)
	ds_write2_b32 v113, v56, v57 offset1:1
	ds_write2_b32 v114, v58, v59 offset1:1
	s_waitcnt vmcnt(0)
	ds_write2_b32 v115, v60, v61 offset1:1
	ds_write2_b32 v116, v62, v63 offset1:1
	s_waitcnt lgkmcnt(0)
	ds_read2_b32 v[6:7], v79 offset1:8
	ds_read2_b32 v[8:9], v79 offset0:65 offset1:73
	ds_read2_b32 v[10:11], v79 offset0:130 offset1:138
	ds_read2_b32 v[12:13], v79 offset0:195 offset1:203
	ds_read2_b32 v[14:15], v117 offset0:4 offset1:12
	s_waitcnt lgkmcnt(4)
	v_bfe_u32 v2, v6, 16, 1
	v_add3_u32 v2, v6, v2, s44
	s_waitcnt lgkmcnt(3)
	v_bfe_u32 v3, v8, 16, 1
	v_lshrrev_b32_e32 v2, 16, v2
	v_add3_u32 v3, v8, v3, s44
	ds_read2_b32 v[16:17], v117 offset0:69 offset1:77
	v_and_or_b32 v2, v3, s45, v2
	s_waitcnt lgkmcnt(3)
	v_bfe_u32 v3, v10, 16, 1
	v_add3_u32 v3, v10, v3, s44
	s_waitcnt lgkmcnt(2)
	v_bfe_u32 v4, v12, 16, 1
	ds_read2_b32 v[18:19], v117 offset0:134 offset1:142
	v_lshrrev_b32_e32 v3, 16, v3
	v_add3_u32 v4, v12, v4, s44
	ds_read2_b32 v[20:21], v117 offset0:199 offset1:207
	v_and_or_b32 v3, v4, s45, v3
	s_waitcnt lgkmcnt(3)
	v_bfe_u32 v4, v14, 16, 1
	v_add3_u32 v4, v14, v4, s44
	s_waitcnt lgkmcnt(2)
	v_bfe_u32 v5, v16, 16, 1
	v_lshrrev_b32_e32 v4, 16, v4
	v_add3_u32 v5, v16, v5, s44
	v_and_or_b32 v4, v5, s45, v4
	s_waitcnt lgkmcnt(1)
	v_bfe_u32 v5, v18, 16, 1
	v_add3_u32 v5, v18, v5, s44
	s_waitcnt lgkmcnt(0)
	v_bfe_u32 v6, v20, 16, 1
	v_lshrrev_b32_e32 v5, 16, v5
	v_add3_u32 v6, v20, v6, s44
	v_lshlrev_b32_e32 v0, 1, v68
	v_mov_b32_e32 v1, v67
	v_and_or_b32 v5, v6, s45, v5
	v_or_b32_e32 v6, s4, v78
	v_lshl_add_u64 v[0:1], s[18:19], 0, v[0:1]
	v_lshlrev_b32_e32 v22, 12, v6
	v_mov_b32_e32 v23, v67
	v_lshl_add_u64 v[22:23], v[0:1], 0, v[22:23]
	global_store_dwordx4 v[22:23], v[2:5], off
	v_bfe_u32 v6, v21, 16, 1
	v_add3_u32 v6, v21, v6, s44
	v_bfe_u32 v2, v7, 16, 1
	v_add3_u32 v2, v7, v2, s44
	v_bfe_u32 v3, v9, 16, 1
	v_lshrrev_b32_e32 v2, 16, v2
	v_add3_u32 v3, v9, v3, s44
	v_and_or_b32 v2, v3, s45, v2
	v_bfe_u32 v3, v11, 16, 1
	v_add3_u32 v3, v11, v3, s44
	v_bfe_u32 v4, v13, 16, 1
	v_lshrrev_b32_e32 v3, 16, v3
	v_add3_u32 v4, v13, v4, s44
	v_and_or_b32 v3, v4, s45, v3
	v_bfe_u32 v4, v15, 16, 1
	v_add3_u32 v4, v15, v4, s44
	v_bfe_u32 v5, v17, 16, 1
	v_lshrrev_b32_e32 v4, 16, v4
	v_add3_u32 v5, v17, v5, s44
	v_and_or_b32 v4, v5, s45, v4
	v_bfe_u32 v5, v19, 16, 1
	v_add3_u32 v5, v19, v5, s44
	v_lshrrev_b32_e32 v5, 16, v5
	v_and_or_b32 v5, v6, s45, v5
	v_or_b32_e32 v6, s4, v80
	v_lshlrev_b32_e32 v6, 12, v6
	v_mov_b32_e32 v7, v67
	ds_read2_b32 v[8:9], v79 offset0:16 offset1:24
	v_lshl_add_u64 v[6:7], v[0:1], 0, v[6:7]
	global_store_dwordx4 v[6:7], v[2:5], off
	ds_read2_b32 v[6:7], v79 offset0:81 offset1:89
	ds_read2_b32 v[10:11], v79 offset0:146 offset1:154
	ds_read2_b32 v[12:13], v79 offset0:211 offset1:219
	s_waitcnt lgkmcnt(3)
	v_bfe_u32 v2, v8, 16, 1
	v_add3_u32 v2, v8, v2, s44
	s_waitcnt lgkmcnt(2)
	v_bfe_u32 v3, v6, 16, 1
	ds_read2_b32 v[14:15], v117 offset0:20 offset1:28
	v_lshrrev_b32_e32 v2, 16, v2
	v_add3_u32 v3, v6, v3, s44
	ds_read2_b32 v[16:17], v117 offset0:85 offset1:93
	v_and_or_b32 v2, v3, s45, v2
	s_waitcnt lgkmcnt(3)
	v_bfe_u32 v3, v10, 16, 1
	v_add3_u32 v3, v10, v3, s44
	s_waitcnt lgkmcnt(2)
	v_bfe_u32 v4, v12, 16, 1
	ds_read2_b32 v[18:19], v117 offset0:150 offset1:158
	v_lshrrev_b32_e32 v3, 16, v3
	v_add3_u32 v4, v12, v4, s44
	ds_read2_b32 v[20:21], v117 offset0:215 offset1:223
	v_and_or_b32 v3, v4, s45, v3
	s_waitcnt lgkmcnt(3)
	v_bfe_u32 v4, v14, 16, 1
	v_add3_u32 v4, v14, v4, s44
	s_waitcnt lgkmcnt(2)
	v_bfe_u32 v5, v16, 16, 1
	v_lshrrev_b32_e32 v4, 16, v4
	v_add3_u32 v5, v16, v5, s44
	v_and_or_b32 v4, v5, s45, v4
	s_waitcnt lgkmcnt(1)
	v_bfe_u32 v5, v18, 16, 1
	v_add3_u32 v5, v18, v5, s44
	s_waitcnt lgkmcnt(0)
	v_bfe_u32 v6, v20, 16, 1
	v_lshrrev_b32_e32 v5, 16, v5
	v_add3_u32 v6, v20, v6, s44
	v_and_or_b32 v5, v6, s45, v5
	v_or_b32_e32 v6, s4, v81
	v_lshlrev_b32_e32 v22, 12, v6
	v_mov_b32_e32 v23, v67
	v_lshl_add_u64 v[22:23], v[0:1], 0, v[22:23]
	global_store_dwordx4 v[22:23], v[2:5], off
	v_bfe_u32 v6, v21, 16, 1
	v_add3_u32 v6, v21, v6, s44
	v_bfe_u32 v2, v9, 16, 1
	v_add3_u32 v2, v9, v2, s44
	v_bfe_u32 v3, v7, 16, 1
	v_lshrrev_b32_e32 v2, 16, v2
	v_add3_u32 v3, v7, v3, s44
	v_and_or_b32 v2, v3, s45, v2
	v_bfe_u32 v3, v11, 16, 1
	v_add3_u32 v3, v11, v3, s44
	v_bfe_u32 v4, v13, 16, 1
	v_lshrrev_b32_e32 v3, 16, v3
	v_add3_u32 v4, v13, v4, s44
	v_and_or_b32 v3, v4, s45, v3
	v_bfe_u32 v4, v15, 16, 1
	v_add3_u32 v4, v15, v4, s44
	v_bfe_u32 v5, v17, 16, 1
	v_lshrrev_b32_e32 v4, 16, v4
	v_add3_u32 v5, v17, v5, s44
	v_and_or_b32 v4, v5, s45, v4
	v_bfe_u32 v5, v19, 16, 1
	v_add3_u32 v5, v19, v5, s44
	v_lshrrev_b32_e32 v5, 16, v5
	v_and_or_b32 v5, v6, s45, v5
	v_or_b32_e32 v6, s4, v82
	v_lshlrev_b32_e32 v6, 12, v6
	v_mov_b32_e32 v7, v67
	ds_read2_b32 v[8:9], v79 offset0:32 offset1:40
	v_lshl_add_u64 v[6:7], v[0:1], 0, v[6:7]
	global_store_dwordx4 v[6:7], v[2:5], off
	ds_read2_b32 v[6:7], v79 offset0:97 offset1:105
	ds_read2_b32 v[10:11], v79 offset0:162 offset1:170
	ds_read2_b32 v[12:13], v79 offset0:227 offset1:235
	s_waitcnt lgkmcnt(3)
	v_bfe_u32 v2, v8, 16, 1
	v_add3_u32 v2, v8, v2, s44
	s_waitcnt lgkmcnt(2)
	v_bfe_u32 v3, v6, 16, 1
	ds_read2_b32 v[14:15], v117 offset0:36 offset1:44
	v_lshrrev_b32_e32 v2, 16, v2
	v_add3_u32 v3, v6, v3, s44
	ds_read2_b32 v[16:17], v117 offset0:101 offset1:109
	v_and_or_b32 v2, v3, s45, v2
	s_waitcnt lgkmcnt(3)
	v_bfe_u32 v3, v10, 16, 1
	v_add3_u32 v3, v10, v3, s44
	s_waitcnt lgkmcnt(2)
	v_bfe_u32 v4, v12, 16, 1
	ds_read2_b32 v[18:19], v117 offset0:166 offset1:174
	v_lshrrev_b32_e32 v3, 16, v3
	v_add3_u32 v4, v12, v4, s44
	ds_read2_b32 v[20:21], v117 offset0:231 offset1:239
	v_and_or_b32 v3, v4, s45, v3
	s_waitcnt lgkmcnt(3)
	v_bfe_u32 v4, v14, 16, 1
	v_add3_u32 v4, v14, v4, s44
	s_waitcnt lgkmcnt(2)
	v_bfe_u32 v5, v16, 16, 1
	v_lshrrev_b32_e32 v4, 16, v4
	v_add3_u32 v5, v16, v5, s44
	v_and_or_b32 v4, v5, s45, v4
	s_waitcnt lgkmcnt(1)
	v_bfe_u32 v5, v18, 16, 1
	v_add3_u32 v5, v18, v5, s44
	s_waitcnt lgkmcnt(0)
	v_bfe_u32 v6, v20, 16, 1
	v_lshrrev_b32_e32 v5, 16, v5
	v_add3_u32 v6, v20, v6, s44
	v_and_or_b32 v5, v6, s45, v5
	v_or_b32_e32 v6, s4, v83
	v_lshlrev_b32_e32 v22, 12, v6
	v_mov_b32_e32 v23, v67
	v_lshl_add_u64 v[22:23], v[0:1], 0, v[22:23]
	global_store_dwordx4 v[22:23], v[2:5], off
	v_bfe_u32 v6, v21, 16, 1
	v_add3_u32 v6, v21, v6, s44
	v_bfe_u32 v2, v9, 16, 1
	v_add3_u32 v2, v9, v2, s44
	v_bfe_u32 v3, v7, 16, 1
	v_lshrrev_b32_e32 v2, 16, v2
	v_add3_u32 v3, v7, v3, s44
	v_and_or_b32 v2, v3, s45, v2
	v_bfe_u32 v3, v11, 16, 1
	v_add3_u32 v3, v11, v3, s44
	v_bfe_u32 v4, v13, 16, 1
	v_lshrrev_b32_e32 v3, 16, v3
	v_add3_u32 v4, v13, v4, s44
	v_and_or_b32 v3, v4, s45, v3
	v_bfe_u32 v4, v15, 16, 1
	v_add3_u32 v4, v15, v4, s44
	v_bfe_u32 v5, v17, 16, 1
	v_lshrrev_b32_e32 v4, 16, v4
	v_add3_u32 v5, v17, v5, s44
	v_and_or_b32 v4, v5, s45, v4
	v_bfe_u32 v5, v19, 16, 1
	v_add3_u32 v5, v19, v5, s44
	v_lshrrev_b32_e32 v5, 16, v5
	v_and_or_b32 v5, v6, s45, v5
	v_or_b32_e32 v6, s4, v84
	v_lshlrev_b32_e32 v6, 12, v6
	v_mov_b32_e32 v7, v67
	ds_read2_b32 v[8:9], v79 offset0:48 offset1:56
	v_lshl_add_u64 v[6:7], v[0:1], 0, v[6:7]
	global_store_dwordx4 v[6:7], v[2:5], off
	ds_read2_b32 v[6:7], v79 offset0:113 offset1:121
	ds_read2_b32 v[10:11], v79 offset0:178 offset1:186
	ds_read2_b32 v[12:13], v79 offset0:243 offset1:251
	s_waitcnt lgkmcnt(3)
	v_bfe_u32 v2, v8, 16, 1
	v_add3_u32 v2, v8, v2, s44
	s_waitcnt lgkmcnt(2)
	v_bfe_u32 v3, v6, 16, 1
	ds_read2_b32 v[14:15], v117 offset0:52 offset1:60
	v_lshrrev_b32_e32 v2, 16, v2
	v_add3_u32 v3, v6, v3, s44
	ds_read2_b32 v[16:17], v117 offset0:117 offset1:125
	v_and_or_b32 v2, v3, s45, v2
	s_waitcnt lgkmcnt(3)
	v_bfe_u32 v3, v10, 16, 1
	v_add3_u32 v3, v10, v3, s44
	s_waitcnt lgkmcnt(2)
	v_bfe_u32 v4, v12, 16, 1
	ds_read2_b32 v[18:19], v117 offset0:182 offset1:190
	v_lshrrev_b32_e32 v3, 16, v3
	v_add3_u32 v4, v12, v4, s44
	ds_read2_b32 v[20:21], v117 offset0:247 offset1:255
	v_and_or_b32 v3, v4, s45, v3
	s_waitcnt lgkmcnt(3)
	v_bfe_u32 v4, v14, 16, 1
	v_add3_u32 v4, v14, v4, s44
	s_waitcnt lgkmcnt(2)
	v_bfe_u32 v5, v16, 16, 1
	v_lshrrev_b32_e32 v4, 16, v4
	v_add3_u32 v5, v16, v5, s44
	v_and_or_b32 v4, v5, s45, v4
	s_waitcnt lgkmcnt(1)
	v_bfe_u32 v5, v18, 16, 1
	v_add3_u32 v5, v18, v5, s44
	s_waitcnt lgkmcnt(0)
	v_bfe_u32 v6, v20, 16, 1
	v_lshrrev_b32_e32 v5, 16, v5
	v_add3_u32 v6, v20, v6, s44
	v_and_or_b32 v5, v6, s45, v5
	v_or_b32_e32 v6, s4, v85
	v_lshlrev_b32_e32 v22, 12, v6
	v_mov_b32_e32 v23, v67
	v_lshl_add_u64 v[22:23], v[0:1], 0, v[22:23]
	global_store_dwordx4 v[22:23], v[2:5], off
	v_bfe_u32 v6, v21, 16, 1
	v_add3_u32 v6, v21, v6, s44
	v_bfe_u32 v2, v9, 16, 1
	v_add3_u32 v2, v9, v2, s44
	v_bfe_u32 v3, v7, 16, 1
	v_lshrrev_b32_e32 v2, 16, v2
	v_add3_u32 v3, v7, v3, s44
	v_and_or_b32 v2, v3, s45, v2
	v_bfe_u32 v3, v11, 16, 1
	v_add3_u32 v3, v11, v3, s44
	v_bfe_u32 v4, v13, 16, 1
	v_lshrrev_b32_e32 v3, 16, v3
	v_add3_u32 v4, v13, v4, s44
	v_and_or_b32 v3, v4, s45, v3
	v_bfe_u32 v4, v15, 16, 1
	v_add3_u32 v4, v15, v4, s44
	v_bfe_u32 v5, v17, 16, 1
	v_lshrrev_b32_e32 v4, 16, v4
	v_add3_u32 v5, v17, v5, s44
	v_and_or_b32 v4, v5, s45, v4
	v_bfe_u32 v5, v19, 16, 1
	v_add3_u32 v5, v19, v5, s44
	v_lshrrev_b32_e32 v5, 16, v5
	v_and_or_b32 v5, v6, s45, v5
	v_or_b32_e32 v6, s4, v86
	v_lshlrev_b32_e32 v6, 12, v6
	v_mov_b32_e32 v7, v67
	v_lshl_add_u64 v[0:1], v[0:1], 0, v[6:7]
	global_store_dwordx4 v[0:1], v[2:5], off
	s_waitcnt lgkmcnt(0)

.LBB0_40:
	s_andn2_b64 vcc, exec, s[18:19]
	s_cbranch_vccnz .LBB0_42
	s_load_dwordx2 s[48:49], s[20:21], 0x90
	s_lshl_b32 s18, s22, 6
	s_add_i32 s4, s22, 0xe000
	s_and_b32 s18, s18, 0xfc0
	s_and_b32 s4, s4, 0xffc0
	s_lshl_b32 s19, s18, 2
	v_or_b32_e32 v58, s4, v76
	s_waitcnt lgkmcnt(0)
	s_add_u32 s48, s48, s19
	s_addc_u32 s49, s49, 0
	v_or_b32_e32 v30, 4, v58
	v_or_b32_e32 v31, 8, v58
	v_lshl_add_u64 v[24:25], s[48:49], 0, v[66:67]
	v_lshlrev_b32_e32 v0, 14, v58
	v_mov_b32_e32 v1, v67
	v_lshlrev_b32_e32 v2, 14, v30
	v_mov_b32_e32 v3, v67
	v_lshlrev_b32_e32 v8, 14, v31
	v_mov_b32_e32 v9, v67
	v_or_b32_e32 v32, 12, v58
	v_lshl_add_u64 v[0:1], v[24:25], 0, v[0:1]
	v_lshl_add_u64 v[2:3], v[24:25], 0, v[2:3]
	v_lshl_add_u64 v[16:17], v[24:25], 0, v[8:9]
	v_lshlrev_b32_e32 v8, 14, v32
	v_or_b32_e32 v38, 16, v58
	global_load_dwordx4 v[4:7], v[0:1], off nt
	s_nop 0
	global_load_dwordx4 v[0:3], v[2:3], off nt
	v_lshl_add_u64 v[18:19], v[24:25], 0, v[8:9]
	global_load_dwordx4 v[12:15], v[16:17], off nt
	global_load_dwordx4 v[8:11], v[18:19], off nt
	v_lshlrev_b32_e32 v16, 14, v38
	v_mov_b32_e32 v17, v67
	v_or_b32_e32 v39, 20, v58
	v_lshl_add_u64 v[26:27], v[24:25], 0, v[16:17]
	v_lshlrev_b32_e32 v16, 14, v39
	v_or_b32_e32 v40, 24, v58
	v_lshl_add_u64 v[28:29], v[24:25], 0, v[16:17]
	global_load_dwordx4 v[20:23], v[26:27], off nt
	global_load_dwordx4 v[16:19], v[28:29], off nt
	v_lshlrev_b32_e32 v26, 14, v40
	v_mov_b32_e32 v27, v67
	v_or_b32_e32 v43, 28, v58
	v_lshl_add_u64 v[34:35], v[24:25], 0, v[26:27]
	v_lshlrev_b32_e32 v26, 14, v43
	v_lshl_add_u64 v[36:37], v[24:25], 0, v[26:27]
	v_lshlrev_b32_e32 v41, 2, v58
	v_lshlrev_b32_e32 v42, 2, v30
	v_lshlrev_b32_e32 v44, 2, v31
	v_lshlrev_b32_e32 v45, 2, v32
	global_load_dwordx4 v[26:29], v[34:35], off nt
	global_load_dwordx4 v[30:33], v[36:37], off nt
	v_lshlrev_b32_e32 v36, 2, v40
	v_lshlrev_b32_e32 v34, 2, v38
	v_lshlrev_b32_e32 v35, 2, v39
	v_lshlrev_b32_e32 v37, 2, v43
	global_load_dword v62, v41, s[8:9]
	global_load_dword v122, v42, s[8:9]
	global_load_dword v124, v44, s[8:9]
	global_load_dword v126, v45, s[8:9]
	global_load_dword v128, v34, s[8:9]
	global_load_dword v130, v35, s[8:9]
	global_load_dword v132, v36, s[8:9]
	global_load_dword v134, v37, s[8:9]
	v_or_b32_e32 v36, 32, v58
	v_lshlrev_b32_e32 v34, 14, v36
	v_mov_b32_e32 v35, v67
	v_or_b32_e32 v46, 36, v58
	v_lshl_add_u64 v[42:43], v[24:25], 0, v[34:35]
	v_lshlrev_b32_e32 v34, 14, v46
	v_or_b32_e32 v61, 40, v58
	v_lshlrev_b32_e32 v59, 2, v36
	v_lshl_add_u64 v[44:45], v[24:25], 0, v[34:35]
	global_load_dwordx4 v[34:37], v[42:43], off nt
	global_load_dwordx4 v[38:41], v[44:45], off nt
	v_lshlrev_b32_e32 v42, 14, v61
	v_mov_b32_e32 v43, v67
	v_or_b32_e32 v63, 44, v58
	v_lshl_add_u64 v[50:51], v[24:25], 0, v[42:43]
	v_lshlrev_b32_e32 v42, 14, v63
	v_lshl_add_u64 v[52:53], v[24:25], 0, v[42:43]
	v_or_b32_e32 v118, 48, v58
	v_or_b32_e32 v119, 52, v58
	v_lshlrev_b32_e32 v60, 2, v46
	global_load_dwordx4 v[42:45], v[50:51], off nt
	global_load_dwordx4 v[46:49], v[52:53], off nt
	v_lshlrev_b32_e32 v50, 14, v118
	v_mov_b32_e32 v51, v67
	v_lshlrev_b32_e32 v52, 14, v119
	v_mov_b32_e32 v53, v67
	v_or_b32_e32 v120, 56, v58
	v_lshl_add_u64 v[50:51], v[24:25], 0, v[50:51]
	v_lshl_add_u64 v[54:55], v[24:25], 0, v[52:53]
	v_or_b32_e32 v121, 60, v58
	v_lshlrev_b32_e32 v58, 2, v61
	v_lshlrev_b32_e32 v61, 2, v63
	v_lshlrev_b32_e32 v63, 2, v118
	v_lshlrev_b32_e32 v118, 2, v119
	v_lshlrev_b32_e32 v119, 2, v120
	global_load_dwordx4 v[50:53], v[50:51], off nt
	s_nop 0
	global_load_dwordx4 v[54:57], v[54:55], off nt
	v_lshlrev_b32_e32 v123, 2, v121
	global_load_dword v136, v59, s[8:9]
	global_load_dword v138, v60, s[8:9]
	global_load_dword v140, v58, s[8:9]
	global_load_dword v142, v61, s[8:9]
	global_load_dword v144, v63, s[8:9]
	global_load_dword v146, v118, s[8:9]
	global_load_dword v148, v119, s[8:9]
	global_load_dword v150, v123, s[8:9]
	v_lshlrev_b32_e32 v58, 14, v120
	v_mov_b32_e32 v59, v67
	v_lshlrev_b32_e32 v118, 14, v121
	v_mov_b32_e32 v119, v67
	v_lshl_add_u64 v[58:59], v[24:25], 0, v[58:59]
	v_lshl_add_u64 v[24:25], v[24:25], 0, v[118:119]
	global_load_dwordx4 v[58:61], v[58:59], off nt
	s_lshl_b32 s4, s4, 1
	global_load_dwordx4 v[118:121], v[24:25], off nt
	s_waitcnt vmcnt(23)
	v_pk_mul_f32 v[4:5], v[4:5], v[62:63] op_sel_hi:[1,0]
	v_pk_mul_f32 v[6:7], v[6:7], v[62:63] op_sel_hi:[1,0]
	s_waitcnt vmcnt(22)
	v_pk_mul_f32 v[2:3], v[2:3], v[122:123] op_sel_hi:[1,0]
	v_pk_mul_f32 v[0:1], v[0:1], v[122:123] op_sel_hi:[1,0]
	s_waitcnt vmcnt(21)
	v_pk_mul_f32 v[14:15], v[14:15], v[124:125] op_sel_hi:[1,0]
	v_pk_mul_f32 v[12:13], v[12:13], v[124:125] op_sel_hi:[1,0]
	s_waitcnt vmcnt(20)
	v_pk_mul_f32 v[10:11], v[10:11], v[126:127] op_sel_hi:[1,0]
	v_pk_mul_f32 v[8:9], v[8:9], v[126:127] op_sel_hi:[1,0]
	s_waitcnt vmcnt(19)
	v_pk_mul_f32 v[22:23], v[22:23], v[128:129] op_sel_hi:[1,0]
	v_pk_mul_f32 v[20:21], v[20:21], v[128:129] op_sel_hi:[1,0]
	s_waitcnt vmcnt(18)
	v_pk_mul_f32 v[18:19], v[18:19], v[130:131] op_sel_hi:[1,0]
	v_pk_mul_f32 v[16:17], v[16:17], v[130:131] op_sel_hi:[1,0]
	s_waitcnt vmcnt(17)
	v_pk_mul_f32 v[24:25], v[28:29], v[132:133] op_sel_hi:[1,0]
	v_pk_mul_f32 v[26:27], v[26:27], v[132:133] op_sel_hi:[1,0]
	s_waitcnt vmcnt(16)
	v_pk_mul_f32 v[28:29], v[32:33], v[134:135] op_sel_hi:[1,0]
	v_pk_mul_f32 v[30:31], v[30:31], v[134:135] op_sel_hi:[1,0]
	s_waitcnt vmcnt(9)
	v_pk_mul_f32 v[32:33], v[36:37], v[136:137] op_sel_hi:[1,0]
	v_pk_mul_f32 v[34:35], v[34:35], v[136:137] op_sel_hi:[1,0]
	s_waitcnt vmcnt(8)
	v_pk_mul_f32 v[36:37], v[40:41], v[138:139] op_sel_hi:[1,0]
	v_pk_mul_f32 v[38:39], v[38:39], v[138:139] op_sel_hi:[1,0]
	s_waitcnt vmcnt(7)
	v_pk_mul_f32 v[40:41], v[44:45], v[140:141] op_sel_hi:[1,0]
	v_pk_mul_f32 v[42:43], v[42:43], v[140:141] op_sel_hi:[1,0]
	s_waitcnt vmcnt(6)
	v_pk_mul_f32 v[44:45], v[48:49], v[142:143] op_sel_hi:[1,0]
	v_pk_mul_f32 v[46:47], v[46:47], v[142:143] op_sel_hi:[1,0]
	s_waitcnt vmcnt(5)
	v_pk_mul_f32 v[48:49], v[52:53], v[144:145] op_sel_hi:[1,0]
	v_pk_mul_f32 v[50:51], v[50:51], v[144:145] op_sel_hi:[1,0]
	s_waitcnt vmcnt(4)
	v_pk_mul_f32 v[52:53], v[56:57], v[146:147] op_sel_hi:[1,0]
	v_pk_mul_f32 v[54:55], v[54:55], v[146:147] op_sel_hi:[1,0]
	s_waitcnt vmcnt(1)
	v_pk_mul_f32 v[56:57], v[60:61], v[148:149] op_sel_hi:[1,0]
	v_pk_mul_f32 v[58:59], v[58:59], v[148:149] op_sel_hi:[1,0]
	s_waitcnt vmcnt(0)
	v_pk_mul_f32 v[60:61], v[120:121], v[150:151] op_sel_hi:[1,0]
	v_pk_mul_f32 v[62:63], v[118:119], v[150:151] op_sel_hi:[1,0]
	ds_write2_b32 v77, v4, v5 offset1:1
	ds_write2_b32 v77, v6, v7 offset0:2 offset1:3
	ds_write2_b32 v87, v0, v1 offset1:1
	ds_write2_b32 v88, v2, v3 offset1:1
	ds_write2_b32 v89, v12, v13 offset1:1
	ds_write2_b32 v90, v14, v15 offset1:1
	ds_write2_b32 v91, v8, v9 offset1:1
	ds_write2_b32 v92, v10, v11 offset1:1
	ds_write2_b32 v93, v20, v21 offset1:1
	ds_write2_b32 v94, v22, v23 offset1:1
	ds_write2_b32 v95, v16, v17 offset1:1
	ds_write2_b32 v96, v18, v19 offset1:1
	ds_write2_b32 v97, v26, v27 offset1:1
	ds_write2_b32 v98, v24, v25 offset1:1
	ds_write2_b32 v99, v30, v31 offset1:1
	ds_write2_b32 v100, v28, v29 offset1:1
	ds_write2_b32 v101, v34, v35 offset1:1
	ds_write2_b32 v102, v32, v33 offset1:1
	ds_write2_b32 v103, v38, v39 offset1:1
	ds_write2_b32 v104, v36, v37 offset1:1
	ds_write2_b32 v105, v42, v43 offset1:1
	ds_write2_b32 v106, v40, v41 offset1:1
	ds_write2_b32 v107, v46, v47 offset1:1
	ds_write2_b32 v108, v44, v45 offset1:1
	ds_write2_b32 v109, v50, v51 offset1:1
	ds_write2_b32 v110, v48, v49 offset1:1
	ds_write2_b32 v111, v54, v55 offset1:1
	ds_write2_b32 v112, v52, v53 offset1:1
	ds_write2_b32 v113, v58, v59 offset1:1
	ds_write2_b32 v114, v56, v57 offset1:1
	ds_write2_b32 v115, v62, v63 offset1:1
	ds_write2_b32 v116, v60, v61 offset1:1
	s_waitcnt lgkmcnt(0)
	ds_read2_b32 v[6:7], v79 offset1:8
	ds_read2_b32 v[8:9], v79 offset0:65 offset1:73
	ds_read2_b32 v[10:11], v79 offset0:130 offset1:138
	ds_read2_b32 v[12:13], v79 offset0:195 offset1:203
	ds_read2_b32 v[14:15], v117 offset0:4 offset1:12
	s_waitcnt lgkmcnt(4)
	v_bfe_u32 v2, v6, 16, 1
	v_add3_u32 v2, v6, v2, s44
	s_waitcnt lgkmcnt(3)
	v_bfe_u32 v3, v8, 16, 1
	v_lshrrev_b32_e32 v2, 16, v2
	v_add3_u32 v3, v8, v3, s44
	ds_read2_b32 v[16:17], v117 offset0:69 offset1:77
	v_and_or_b32 v2, v3, s45, v2
	s_waitcnt lgkmcnt(3)
	v_bfe_u32 v3, v10, 16, 1
	v_add3_u32 v3, v10, v3, s44
	s_waitcnt lgkmcnt(2)
	v_bfe_u32 v4, v12, 16, 1
	ds_read2_b32 v[18:19], v117 offset0:134 offset1:142
	v_lshrrev_b32_e32 v3, 16, v3
	v_add3_u32 v4, v12, v4, s44
	ds_read2_b32 v[20:21], v117 offset0:199 offset1:207
	v_and_or_b32 v3, v4, s45, v3
	s_waitcnt lgkmcnt(3)
	v_bfe_u32 v4, v14, 16, 1
	v_add3_u32 v4, v14, v4, s44
	s_waitcnt lgkmcnt(2)
	v_bfe_u32 v5, v16, 16, 1
	v_lshrrev_b32_e32 v4, 16, v4
	v_add3_u32 v5, v16, v5, s44
	v_and_or_b32 v4, v5, s45, v4
	s_waitcnt lgkmcnt(1)
	v_bfe_u32 v5, v18, 16, 1
	v_add3_u32 v5, v18, v5, s44
	s_waitcnt lgkmcnt(0)
	v_bfe_u32 v6, v20, 16, 1
	v_lshrrev_b32_e32 v5, 16, v5
	v_add3_u32 v6, v20, v6, s44
	v_and_or_b32 v5, v6, s45, v5
	v_or_b32_e32 v6, s18, v78
	v_lshl_add_u64 v[0:1], v[70:71], 0, s[4:5]
	v_lshlrev_b32_e32 v22, 12, v6
	v_mov_b32_e32 v23, v67
	v_lshl_add_u64 v[22:23], v[0:1], 0, v[22:23]
	global_store_dwordx4 v[22:23], v[2:5], off
	v_bfe_u32 v6, v21, 16, 1
	v_add3_u32 v6, v21, v6, s44
	v_bfe_u32 v2, v7, 16, 1
	v_add3_u32 v2, v7, v2, s44
	v_bfe_u32 v3, v9, 16, 1
	v_lshrrev_b32_e32 v2, 16, v2
	v_add3_u32 v3, v9, v3, s44
	v_and_or_b32 v2, v3, s45, v2
	v_bfe_u32 v3, v11, 16, 1
	v_add3_u32 v3, v11, v3, s44
	v_bfe_u32 v4, v13, 16, 1
	v_lshrrev_b32_e32 v3, 16, v3
	v_add3_u32 v4, v13, v4, s44
	v_and_or_b32 v3, v4, s45, v3
	v_bfe_u32 v4, v15, 16, 1
	v_add3_u32 v4, v15, v4, s44
	v_bfe_u32 v5, v17, 16, 1
	v_lshrrev_b32_e32 v4, 16, v4
	v_add3_u32 v5, v17, v5, s44
	v_and_or_b32 v4, v5, s45, v4
	v_bfe_u32 v5, v19, 16, 1
	v_add3_u32 v5, v19, v5, s44
	v_lshrrev_b32_e32 v5, 16, v5
	v_and_or_b32 v5, v6, s45, v5
	v_or_b32_e32 v6, s18, v80
	v_lshlrev_b32_e32 v6, 12, v6
	v_mov_b32_e32 v7, v67
	ds_read2_b32 v[8:9], v79 offset0:16 offset1:24
	v_lshl_add_u64 v[6:7], v[0:1], 0, v[6:7]
	global_store_dwordx4 v[6:7], v[2:5], off
	ds_read2_b32 v[6:7], v79 offset0:81 offset1:89
	ds_read2_b32 v[10:11], v79 offset0:146 offset1:154
	ds_read2_b32 v[12:13], v79 offset0:211 offset1:219
	s_waitcnt lgkmcnt(3)
	v_bfe_u32 v2, v8, 16, 1
	v_add3_u32 v2, v8, v2, s44
	s_waitcnt lgkmcnt(2)
	v_bfe_u32 v3, v6, 16, 1
	ds_read2_b32 v[14:15], v117 offset0:20 offset1:28
	v_lshrrev_b32_e32 v2, 16, v2
	v_add3_u32 v3, v6, v3, s44
	ds_read2_b32 v[16:17], v117 offset0:85 offset1:93
	v_and_or_b32 v2, v3, s45, v2
	s_waitcnt lgkmcnt(3)
	v_bfe_u32 v3, v10, 16, 1
	v_add3_u32 v3, v10, v3, s44
	s_waitcnt lgkmcnt(2)
	v_bfe_u32 v4, v12, 16, 1
	ds_read2_b32 v[18:19], v117 offset0:150 offset1:158
	v_lshrrev_b32_e32 v3, 16, v3
	v_add3_u32 v4, v12, v4, s44
	ds_read2_b32 v[20:21], v117 offset0:215 offset1:223
	v_and_or_b32 v3, v4, s45, v3
	s_waitcnt lgkmcnt(3)
	v_bfe_u32 v4, v14, 16, 1
	v_add3_u32 v4, v14, v4, s44
	s_waitcnt lgkmcnt(2)
	v_bfe_u32 v5, v16, 16, 1
	v_lshrrev_b32_e32 v4, 16, v4
	v_add3_u32 v5, v16, v5, s44
	v_and_or_b32 v4, v5, s45, v4
	s_waitcnt lgkmcnt(1)
	v_bfe_u32 v5, v18, 16, 1
	v_add3_u32 v5, v18, v5, s44
	s_waitcnt lgkmcnt(0)
	v_bfe_u32 v6, v20, 16, 1
	v_lshrrev_b32_e32 v5, 16, v5
	v_add3_u32 v6, v20, v6, s44
	v_and_or_b32 v5, v6, s45, v5
	v_or_b32_e32 v6, s18, v81
	v_lshlrev_b32_e32 v22, 12, v6
	v_mov_b32_e32 v23, v67
	v_lshl_add_u64 v[22:23], v[0:1], 0, v[22:23]
	global_store_dwordx4 v[22:23], v[2:5], off
	v_bfe_u32 v6, v21, 16, 1
	v_add3_u32 v6, v21, v6, s44
	v_bfe_u32 v2, v9, 16, 1
	v_add3_u32 v2, v9, v2, s44
	v_bfe_u32 v3, v7, 16, 1
	v_lshrrev_b32_e32 v2, 16, v2
	v_add3_u32 v3, v7, v3, s44
	v_and_or_b32 v2, v3, s45, v2
	v_bfe_u32 v3, v11, 16, 1
	v_add3_u32 v3, v11, v3, s44
	v_bfe_u32 v4, v13, 16, 1
	v_lshrrev_b32_e32 v3, 16, v3
	v_add3_u32 v4, v13, v4, s44
	v_and_or_b32 v3, v4, s45, v3
	v_bfe_u32 v4, v15, 16, 1
	v_add3_u32 v4, v15, v4, s44
	v_bfe_u32 v5, v17, 16, 1
	v_lshrrev_b32_e32 v4, 16, v4
	v_add3_u32 v5, v17, v5, s44
	v_and_or_b32 v4, v5, s45, v4
	v_bfe_u32 v5, v19, 16, 1
	v_add3_u32 v5, v19, v5, s44
	v_lshrrev_b32_e32 v5, 16, v5
	v_and_or_b32 v5, v6, s45, v5
	v_or_b32_e32 v6, s18, v82
	v_lshlrev_b32_e32 v6, 12, v6
	v_mov_b32_e32 v7, v67
	ds_read2_b32 v[8:9], v79 offset0:32 offset1:40
	v_lshl_add_u64 v[6:7], v[0:1], 0, v[6:7]
	global_store_dwordx4 v[6:7], v[2:5], off
	ds_read2_b32 v[6:7], v79 offset0:97 offset1:105
	ds_read2_b32 v[10:11], v79 offset0:162 offset1:170
	ds_read2_b32 v[12:13], v79 offset0:227 offset1:235
	s_waitcnt lgkmcnt(3)
	v_bfe_u32 v2, v8, 16, 1
	v_add3_u32 v2, v8, v2, s44
	s_waitcnt lgkmcnt(2)
	v_bfe_u32 v3, v6, 16, 1
	ds_read2_b32 v[14:15], v117 offset0:36 offset1:44
	v_lshrrev_b32_e32 v2, 16, v2
	v_add3_u32 v3, v6, v3, s44
	ds_read2_b32 v[16:17], v117 offset0:101 offset1:109
	v_and_or_b32 v2, v3, s45, v2
	s_waitcnt lgkmcnt(3)
	v_bfe_u32 v3, v10, 16, 1
	v_add3_u32 v3, v10, v3, s44
	s_waitcnt lgkmcnt(2)
	v_bfe_u32 v4, v12, 16, 1
	ds_read2_b32 v[18:19], v117 offset0:166 offset1:174
	v_lshrrev_b32_e32 v3, 16, v3
	v_add3_u32 v4, v12, v4, s44
	ds_read2_b32 v[20:21], v117 offset0:231 offset1:239
	v_and_or_b32 v3, v4, s45, v3
	s_waitcnt lgkmcnt(3)
	v_bfe_u32 v4, v14, 16, 1
	v_add3_u32 v4, v14, v4, s44
	s_waitcnt lgkmcnt(2)
	v_bfe_u32 v5, v16, 16, 1
	v_lshrrev_b32_e32 v4, 16, v4
	v_add3_u32 v5, v16, v5, s44
	v_and_or_b32 v4, v5, s45, v4
	s_waitcnt lgkmcnt(1)
	v_bfe_u32 v5, v18, 16, 1
	v_add3_u32 v5, v18, v5, s44
	s_waitcnt lgkmcnt(0)
	v_bfe_u32 v6, v20, 16, 1
	v_lshrrev_b32_e32 v5, 16, v5
	v_add3_u32 v6, v20, v6, s44
	v_and_or_b32 v5, v6, s45, v5
	v_or_b32_e32 v6, s18, v83
	v_lshlrev_b32_e32 v22, 12, v6
	v_mov_b32_e32 v23, v67
	v_lshl_add_u64 v[22:23], v[0:1], 0, v[22:23]
	global_store_dwordx4 v[22:23], v[2:5], off
	v_bfe_u32 v6, v21, 16, 1
	v_add3_u32 v6, v21, v6, s44
	v_bfe_u32 v2, v9, 16, 1
	v_add3_u32 v2, v9, v2, s44
	v_bfe_u32 v3, v7, 16, 1
	v_lshrrev_b32_e32 v2, 16, v2
	v_add3_u32 v3, v7, v3, s44
	v_and_or_b32 v2, v3, s45, v2
	v_bfe_u32 v3, v11, 16, 1
	v_add3_u32 v3, v11, v3, s44
	v_bfe_u32 v4, v13, 16, 1
	v_lshrrev_b32_e32 v3, 16, v3
	v_add3_u32 v4, v13, v4, s44
	v_and_or_b32 v3, v4, s45, v3
	v_bfe_u32 v4, v15, 16, 1
	v_add3_u32 v4, v15, v4, s44
	v_bfe_u32 v5, v17, 16, 1
	v_lshrrev_b32_e32 v4, 16, v4
	v_add3_u32 v5, v17, v5, s44
	v_and_or_b32 v4, v5, s45, v4
	v_bfe_u32 v5, v19, 16, 1
	v_add3_u32 v5, v19, v5, s44
	v_lshrrev_b32_e32 v5, 16, v5
	v_and_or_b32 v5, v6, s45, v5
	v_or_b32_e32 v6, s18, v84
	v_lshlrev_b32_e32 v6, 12, v6
	v_mov_b32_e32 v7, v67
	ds_read2_b32 v[8:9], v79 offset0:48 offset1:56
	v_lshl_add_u64 v[6:7], v[0:1], 0, v[6:7]
	global_store_dwordx4 v[6:7], v[2:5], off
	ds_read2_b32 v[6:7], v79 offset0:113 offset1:121
	ds_read2_b32 v[10:11], v79 offset0:178 offset1:186
	ds_read2_b32 v[12:13], v79 offset0:243 offset1:251
	s_waitcnt lgkmcnt(3)
	v_bfe_u32 v2, v8, 16, 1
	v_add3_u32 v2, v8, v2, s44
	s_waitcnt lgkmcnt(2)
	v_bfe_u32 v3, v6, 16, 1
	ds_read2_b32 v[14:15], v117 offset0:52 offset1:60
	v_lshrrev_b32_e32 v2, 16, v2
	v_add3_u32 v3, v6, v3, s44
	ds_read2_b32 v[16:17], v117 offset0:117 offset1:125
	v_and_or_b32 v2, v3, s45, v2
	s_waitcnt lgkmcnt(3)
	v_bfe_u32 v3, v10, 16, 1
	v_add3_u32 v3, v10, v3, s44
	s_waitcnt lgkmcnt(2)
	v_bfe_u32 v4, v12, 16, 1
	ds_read2_b32 v[18:19], v117 offset0:182 offset1:190
	v_lshrrev_b32_e32 v3, 16, v3
	v_add3_u32 v4, v12, v4, s44
	ds_read2_b32 v[20:21], v117 offset0:247 offset1:255
	v_and_or_b32 v3, v4, s45, v3
	s_waitcnt lgkmcnt(3)
	v_bfe_u32 v4, v14, 16, 1
	v_add3_u32 v4, v14, v4, s44
	s_waitcnt lgkmcnt(2)
	v_bfe_u32 v5, v16, 16, 1
	v_lshrrev_b32_e32 v4, 16, v4
	v_add3_u32 v5, v16, v5, s44
	v_and_or_b32 v4, v5, s45, v4
	s_waitcnt lgkmcnt(1)
	v_bfe_u32 v5, v18, 16, 1
	v_add3_u32 v5, v18, v5, s44
	s_waitcnt lgkmcnt(0)
	v_bfe_u32 v6, v20, 16, 1
	v_lshrrev_b32_e32 v5, 16, v5
	v_add3_u32 v6, v20, v6, s44
	v_and_or_b32 v5, v6, s45, v5
	v_or_b32_e32 v6, s18, v85
	v_lshlrev_b32_e32 v22, 12, v6
	v_mov_b32_e32 v23, v67
	v_lshl_add_u64 v[22:23], v[0:1], 0, v[22:23]
	global_store_dwordx4 v[22:23], v[2:5], off
	v_bfe_u32 v6, v21, 16, 1
	v_add3_u32 v6, v21, v6, s44
	v_bfe_u32 v2, v9, 16, 1
	v_add3_u32 v2, v9, v2, s44
	v_bfe_u32 v3, v7, 16, 1
	v_lshrrev_b32_e32 v2, 16, v2
	v_add3_u32 v3, v7, v3, s44
	v_and_or_b32 v2, v3, s45, v2
	v_bfe_u32 v3, v11, 16, 1
	v_add3_u32 v3, v11, v3, s44
	v_bfe_u32 v4, v13, 16, 1
	v_lshrrev_b32_e32 v3, 16, v3
	v_add3_u32 v4, v13, v4, s44
	v_and_or_b32 v3, v4, s45, v3
	v_bfe_u32 v4, v15, 16, 1
	v_add3_u32 v4, v15, v4, s44
	v_bfe_u32 v5, v17, 16, 1
	v_lshrrev_b32_e32 v4, 16, v4
	v_add3_u32 v5, v17, v5, s44
	v_and_or_b32 v4, v5, s45, v4
	v_bfe_u32 v5, v19, 16, 1
	v_add3_u32 v5, v19, v5, s44
	v_lshrrev_b32_e32 v5, 16, v5
	v_and_or_b32 v5, v6, s45, v5
	v_or_b32_e32 v6, s18, v86
	v_lshlrev_b32_e32 v6, 12, v6
	v_mov_b32_e32 v7, v67
	v_lshl_add_u64 v[0:1], v[0:1], 0, v[6:7]
	global_store_dwordx4 v[0:1], v[2:5], off
	s_waitcnt lgkmcnt(0)

.LBB0_43:
	s_andn2_b64 vcc, exec, s[18:19]
	s_cbranch_vccnz .LBB0_45
	s_load_dwordx2 s[48:49], s[20:21], 0x70
	s_add_i32 s4, s22, 0xf000
	s_lshl_b32 s18, s22, 6
	s_lshr_b32 s4, s4, 1
	s_and_b32 s18, s18, 0x1fc0
	s_and_b32 s4, s4, 0x7fc0
	s_lshl_b32 s19, s18, 2
	v_or_b32_e32 v28, s4, v76
	s_waitcnt lgkmcnt(0)
	s_add_u32 s48, s48, s19
	s_addc_u32 s49, s49, 0
	v_mul_u32_u24_e32 v0, 0x2010, v28
	v_lshl_add_u64 v[60:61], s[48:49], 0, v[66:67]
	v_lshlrev_b32_e32 v62, 2, v0
	v_mov_b32_e32 v63, v67
	v_lshl_add_u64 v[8:9], v[60:61], 0, v[62:63]
	v_add_co_u32_e32 v4, vcc, s30, v8
	v_add_u32_e32 v10, 0x60300, v62
	s_nop 0
	v_addc_co_u32_e32 v5, vcc, 0, v9, vcc
	global_load_dwordx4 v[0:3], v[8:9], off nt
	s_nop 0
	global_load_dwordx4 v[4:7], v[4:5], off offset:256 nt
	v_add_co_u32_e32 v8, vcc, s36, v8
	v_mov_b32_e32 v11, v67
	v_add_u32_e32 v16, 0x80400, v62
	v_mov_b32_e32 v17, v67
	v_addc_co_u32_e32 v9, vcc, 0, v9, vcc
	v_lshl_add_u64 v[10:11], v[60:61], 0, v[10:11]
	v_lshl_add_u64 v[24:25], v[60:61], 0, v[16:17]
	v_add_u32_e32 v16, 0xa0500, v62
	global_load_dwordx4 v[12:15], v[8:9], off offset:512 nt
	s_nop 0
	global_load_dwordx4 v[8:11], v[10:11], off nt
	v_lshl_add_u64 v[26:27], v[60:61], 0, v[16:17]
	global_load_dwordx4 v[20:23], v[24:25], off nt
	global_load_dwordx4 v[16:19], v[26:27], off nt
	v_add_u32_e32 v24, 0xc0600, v62
	v_mov_b32_e32 v25, v67
	v_lshlrev_b32_e32 v119, 2, v28
	v_lshl_add_u64 v[32:33], v[60:61], 0, v[24:25]
	v_add_u32_e32 v24, 0xe0700, v62
	global_load_dword v118, v119, s[10:11]
	v_lshl_add_u64 v[34:35], v[60:61], 0, v[24:25]
	global_load_dwordx4 v[24:27], v[32:33], off nt
	global_load_dwordx4 v[28:31], v[34:35], off nt
	v_add_u32_e32 v32, 0x100800, v62
	v_mov_b32_e32 v33, v67
	v_or_b32_e32 v36, 16, v119
	v_lshl_add_u64 v[40:41], v[60:61], 0, v[32:33]
	v_or_b32_e32 v32, 64, v119
	v_or_b32_e32 v33, 0x50, v119
	v_or_b32_e32 v37, 32, v119
	v_or_b32_e32 v38, 48, v119
	v_or_b32_e32 v34, 0x60, v119
	v_or_b32_e32 v35, 0x70, v119
	v_or_b32_e32 v39, 0x80, v119
	global_load_dword v120, v36, s[10:11]
	global_load_dword v122, v37, s[10:11]
	global_load_dword v124, v38, s[10:11]
	global_load_dword v126, v32, s[10:11]
	global_load_dword v128, v33, s[10:11]
	global_load_dword v130, v34, s[10:11]
	global_load_dword v132, v35, s[10:11]
	global_load_dword v134, v39, s[10:11]
	v_add_u32_e32 v32, 0x120900, v62
	v_mov_b32_e32 v33, v67
	v_lshl_add_u64 v[42:43], v[60:61], 0, v[32:33]
	v_or_b32_e32 v44, 0x90, v119
	global_load_dword v136, v44, s[10:11]
	global_load_dwordx4 v[32:35], v[40:41], off nt
	global_load_dwordx4 v[36:39], v[42:43], off nt
	v_mov_b32_e32 v41, v67
	v_mov_b32_e32 v43, v67
	v_mov_b32_e32 v45, v67
	v_mov_b32_e32 v47, v67
	v_add_u32_e32 v40, 0x140a00, v62
	v_add_u32_e32 v42, 0x160b00, v62
	v_add_u32_e32 v44, 0x180c00, v62
	v_add_u32_e32 v46, 0x1a0d00, v62
	v_add_u32_e32 v56, 0x1c0e00, v62
	v_mov_b32_e32 v57, v67
	v_add_u32_e32 v62, 0x1e0f00, v62
	v_lshl_add_u64 v[48:49], v[60:61], 0, v[40:41]
	v_lshl_add_u64 v[50:51], v[60:61], 0, v[42:43]
	v_lshl_add_u64 v[52:53], v[60:61], 0, v[44:45]
	v_lshl_add_u64 v[54:55], v[60:61], 0, v[46:47]
	v_lshl_add_u64 v[56:57], v[60:61], 0, v[56:57]
	v_lshl_add_u64 v[60:61], v[60:61], 0, v[62:63]
	v_or_b32_e32 v62, 0xa0, v119
	v_or_b32_e32 v63, 0xb0, v119
	global_load_dwordx4 v[40:43], v[48:49], off nt
	global_load_dwordx4 v[44:47], v[50:51], off nt
	s_nop 0
	global_load_dwordx4 v[48:51], v[52:53], off nt
	s_nop 0
	global_load_dwordx4 v[52:55], v[54:55], off nt
	s_lshl_b32 s4, s4, 1
	global_load_dwordx4 v[56:59], v[56:57], off nt
	s_nop 0
	global_load_dword v138, v62, s[10:11]
	global_load_dword v140, v63, s[10:11]
	v_or_b32_e32 v62, 0xc0, v119
	v_or_b32_e32 v63, 0xd0, v119
	global_load_dword v142, v62, s[10:11]
	global_load_dword v144, v63, s[10:11]
	v_or_b32_e32 v62, 0xe0, v119
	v_or_b32_e32 v63, 0xf0, v119
	global_load_dword v146, v62, s[10:11]
	global_load_dword v148, v63, s[10:11]
	s_nop 0
	global_load_dwordx4 v[60:63], v[60:61], off nt
	s_waitcnt vmcnt(25)
	v_pk_mul_f32 v[0:1], v[0:1], v[118:119] op_sel_hi:[1,0]
	v_pk_mul_f32 v[2:3], v[2:3], v[118:119] op_sel_hi:[1,0]
	s_waitcnt vmcnt(22)
	v_pk_mul_f32 v[6:7], v[6:7], v[120:121] op_sel_hi:[1,0]
	v_pk_mul_f32 v[4:5], v[4:5], v[120:121] op_sel_hi:[1,0]
	s_waitcnt vmcnt(21)
	v_pk_mul_f32 v[14:15], v[14:15], v[122:123] op_sel_hi:[1,0]
	v_pk_mul_f32 v[12:13], v[12:13], v[122:123] op_sel_hi:[1,0]
	s_waitcnt vmcnt(20)
	v_pk_mul_f32 v[10:11], v[10:11], v[124:125] op_sel_hi:[1,0]
	v_pk_mul_f32 v[8:9], v[8:9], v[124:125] op_sel_hi:[1,0]
	s_waitcnt vmcnt(19)
	v_pk_mul_f32 v[22:23], v[22:23], v[126:127] op_sel_hi:[1,0]
	v_pk_mul_f32 v[20:21], v[20:21], v[126:127] op_sel_hi:[1,0]
	s_waitcnt vmcnt(18)
	v_pk_mul_f32 v[18:19], v[18:19], v[128:129] op_sel_hi:[1,0]
	v_pk_mul_f32 v[16:17], v[16:17], v[128:129] op_sel_hi:[1,0]
	s_waitcnt vmcnt(17)
	v_pk_mul_f32 v[26:27], v[26:27], v[130:131] op_sel_hi:[1,0]
	v_pk_mul_f32 v[24:25], v[24:25], v[130:131] op_sel_hi:[1,0]
	s_waitcnt vmcnt(16)
	v_pk_mul_f32 v[30:31], v[30:31], v[132:133] op_sel_hi:[1,0]
	v_pk_mul_f32 v[28:29], v[28:29], v[132:133] op_sel_hi:[1,0]
	s_waitcnt vmcnt(13)
	v_pk_mul_f32 v[34:35], v[34:35], v[134:135] op_sel_hi:[1,0]
	v_pk_mul_f32 v[32:33], v[32:33], v[134:135] op_sel_hi:[1,0]
	s_waitcnt vmcnt(12)
	v_pk_mul_f32 v[38:39], v[38:39], v[136:137] op_sel_hi:[1,0]
	v_pk_mul_f32 v[36:37], v[36:37], v[136:137] op_sel_hi:[1,0]
	s_waitcnt vmcnt(6)
	v_pk_mul_f32 v[42:43], v[42:43], v[138:139] op_sel_hi:[1,0]
	v_pk_mul_f32 v[40:41], v[40:41], v[138:139] op_sel_hi:[1,0]
	s_waitcnt vmcnt(5)
	v_pk_mul_f32 v[46:47], v[46:47], v[140:141] op_sel_hi:[1,0]
	v_pk_mul_f32 v[44:45], v[44:45], v[140:141] op_sel_hi:[1,0]
	s_waitcnt vmcnt(4)
	v_pk_mul_f32 v[50:51], v[50:51], v[142:143] op_sel_hi:[1,0]
	v_pk_mul_f32 v[48:49], v[48:49], v[142:143] op_sel_hi:[1,0]
	s_waitcnt vmcnt(3)
	v_pk_mul_f32 v[54:55], v[54:55], v[144:145] op_sel_hi:[1,0]
	v_pk_mul_f32 v[52:53], v[52:53], v[144:145] op_sel_hi:[1,0]
	s_waitcnt vmcnt(2)
	v_pk_mul_f32 v[58:59], v[58:59], v[146:147] op_sel_hi:[1,0]
	v_pk_mul_f32 v[56:57], v[56:57], v[146:147] op_sel_hi:[1,0]
	s_waitcnt vmcnt(0)
	v_pk_mul_f32 v[62:63], v[62:63], v[148:149] op_sel_hi:[1,0]
	v_pk_mul_f32 v[60:61], v[60:61], v[148:149] op_sel_hi:[1,0]
	ds_write2_b32 v77, v0, v1 offset1:1
	ds_write2_b32 v77, v2, v3 offset0:2 offset1:3
	ds_write2_b32 v87, v4, v5 offset1:1
	ds_write2_b32 v88, v6, v7 offset1:1
	ds_write2_b32 v89, v12, v13 offset1:1
	ds_write2_b32 v90, v14, v15 offset1:1
	ds_write2_b32 v91, v8, v9 offset1:1
	ds_write2_b32 v92, v10, v11 offset1:1
	ds_write2_b32 v93, v20, v21 offset1:1
	ds_write2_b32 v94, v22, v23 offset1:1
	ds_write2_b32 v95, v16, v17 offset1:1
	ds_write2_b32 v96, v18, v19 offset1:1
	ds_write2_b32 v97, v24, v25 offset1:1
	ds_write2_b32 v98, v26, v27 offset1:1
	ds_write2_b32 v99, v28, v29 offset1:1
	ds_write2_b32 v100, v30, v31 offset1:1
	ds_write2_b32 v101, v32, v33 offset1:1
	ds_write2_b32 v102, v34, v35 offset1:1
	ds_write2_b32 v103, v36, v37 offset1:1
	ds_write2_b32 v104, v38, v39 offset1:1
	ds_write2_b32 v105, v40, v41 offset1:1
	ds_write2_b32 v106, v42, v43 offset1:1
	ds_write2_b32 v107, v44, v45 offset1:1
	ds_write2_b32 v108, v46, v47 offset1:1
	ds_write2_b32 v109, v48, v49 offset1:1
	ds_write2_b32 v110, v50, v51 offset1:1
	ds_write2_b32 v111, v52, v53 offset1:1
	ds_write2_b32 v112, v54, v55 offset1:1
	ds_write2_b32 v113, v56, v57 offset1:1
	ds_write2_b32 v114, v58, v59 offset1:1
	ds_write2_b32 v115, v60, v61 offset1:1
	ds_write2_b32 v116, v62, v63 offset1:1
	s_waitcnt lgkmcnt(0)
	ds_read2_b32 v[6:7], v79 offset1:8
	ds_read2_b32 v[8:9], v79 offset0:65 offset1:73
	ds_read2_b32 v[10:11], v79 offset0:130 offset1:138
	ds_read2_b32 v[12:13], v79 offset0:195 offset1:203
	ds_read2_b32 v[14:15], v117 offset0:4 offset1:12
	s_waitcnt lgkmcnt(4)
	v_bfe_u32 v2, v6, 16, 1
	v_add3_u32 v2, v6, v2, s44
	s_waitcnt lgkmcnt(3)
	v_bfe_u32 v3, v8, 16, 1
	v_lshrrev_b32_e32 v2, 16, v2
	v_add3_u32 v3, v8, v3, s44
	ds_read2_b32 v[16:17], v117 offset0:69 offset1:77
	v_and_or_b32 v2, v3, s45, v2
	s_waitcnt lgkmcnt(3)
	v_bfe_u32 v3, v10, 16, 1
	v_add3_u32 v3, v10, v3, s44
	s_waitcnt lgkmcnt(2)
	v_bfe_u32 v4, v12, 16, 1
	ds_read2_b32 v[18:19], v117 offset0:134 offset1:142
	v_lshrrev_b32_e32 v3, 16, v3
	v_add3_u32 v4, v12, v4, s44
	ds_read2_b32 v[20:21], v117 offset0:199 offset1:207
	v_and_or_b32 v3, v4, s45, v3
	s_waitcnt lgkmcnt(3)
	v_bfe_u32 v4, v14, 16, 1
	v_add3_u32 v4, v14, v4, s44
	s_waitcnt lgkmcnt(2)
	v_bfe_u32 v5, v16, 16, 1
	v_lshrrev_b32_e32 v4, 16, v4
	v_add3_u32 v5, v16, v5, s44
	v_and_or_b32 v4, v5, s45, v4
	s_waitcnt lgkmcnt(1)
	v_bfe_u32 v5, v18, 16, 1
	v_add3_u32 v5, v18, v5, s44
	s_waitcnt lgkmcnt(0)
	v_bfe_u32 v6, v20, 16, 1
	v_lshrrev_b32_e32 v5, 16, v5
	v_add3_u32 v6, v20, v6, s44
	v_and_or_b32 v5, v6, s45, v5
	v_or_b32_e32 v6, s18, v78
	v_lshl_add_u64 v[0:1], v[72:73], 0, s[4:5]
	v_lshlrev_b32_e32 v22, 12, v6
	v_mov_b32_e32 v23, v67
	v_lshl_add_u64 v[22:23], v[0:1], 0, v[22:23]
	global_store_dwordx4 v[22:23], v[2:5], off
	v_bfe_u32 v6, v21, 16, 1
	v_add3_u32 v6, v21, v6, s44
	v_bfe_u32 v2, v7, 16, 1
	v_add3_u32 v2, v7, v2, s44
	v_bfe_u32 v3, v9, 16, 1
	v_lshrrev_b32_e32 v2, 16, v2
	v_add3_u32 v3, v9, v3, s44
	v_and_or_b32 v2, v3, s45, v2
	v_bfe_u32 v3, v11, 16, 1
	v_add3_u32 v3, v11, v3, s44
	v_bfe_u32 v4, v13, 16, 1
	v_lshrrev_b32_e32 v3, 16, v3
	v_add3_u32 v4, v13, v4, s44
	v_and_or_b32 v3, v4, s45, v3
	v_bfe_u32 v4, v15, 16, 1
	v_add3_u32 v4, v15, v4, s44
	v_bfe_u32 v5, v17, 16, 1
	v_lshrrev_b32_e32 v4, 16, v4
	v_add3_u32 v5, v17, v5, s44
	v_and_or_b32 v4, v5, s45, v4
	v_bfe_u32 v5, v19, 16, 1
	v_add3_u32 v5, v19, v5, s44
	v_lshrrev_b32_e32 v5, 16, v5
	v_and_or_b32 v5, v6, s45, v5
	v_or_b32_e32 v6, s18, v80
	v_lshlrev_b32_e32 v6, 12, v6
	v_mov_b32_e32 v7, v67
	ds_read2_b32 v[8:9], v79 offset0:16 offset1:24
	v_lshl_add_u64 v[6:7], v[0:1], 0, v[6:7]
	global_store_dwordx4 v[6:7], v[2:5], off
	ds_read2_b32 v[6:7], v79 offset0:81 offset1:89
	ds_read2_b32 v[10:11], v79 offset0:146 offset1:154
	ds_read2_b32 v[12:13], v79 offset0:211 offset1:219
	s_waitcnt lgkmcnt(3)
	v_bfe_u32 v2, v8, 16, 1
	v_add3_u32 v2, v8, v2, s44
	s_waitcnt lgkmcnt(2)
	v_bfe_u32 v3, v6, 16, 1
	ds_read2_b32 v[14:15], v117 offset0:20 offset1:28
	v_lshrrev_b32_e32 v2, 16, v2
	v_add3_u32 v3, v6, v3, s44
	ds_read2_b32 v[16:17], v117 offset0:85 offset1:93
	v_and_or_b32 v2, v3, s45, v2
	s_waitcnt lgkmcnt(3)
	v_bfe_u32 v3, v10, 16, 1
	v_add3_u32 v3, v10, v3, s44
	s_waitcnt lgkmcnt(2)
	v_bfe_u32 v4, v12, 16, 1
	ds_read2_b32 v[18:19], v117 offset0:150 offset1:158
	v_lshrrev_b32_e32 v3, 16, v3
	v_add3_u32 v4, v12, v4, s44
	ds_read2_b32 v[20:21], v117 offset0:215 offset1:223
	v_and_or_b32 v3, v4, s45, v3
	s_waitcnt lgkmcnt(3)
	v_bfe_u32 v4, v14, 16, 1
	v_add3_u32 v4, v14, v4, s44
	s_waitcnt lgkmcnt(2)
	v_bfe_u32 v5, v16, 16, 1
	v_lshrrev_b32_e32 v4, 16, v4
	v_add3_u32 v5, v16, v5, s44
	v_and_or_b32 v4, v5, s45, v4
	s_waitcnt lgkmcnt(1)
	v_bfe_u32 v5, v18, 16, 1
	v_add3_u32 v5, v18, v5, s44
	s_waitcnt lgkmcnt(0)
	v_bfe_u32 v6, v20, 16, 1
	v_lshrrev_b32_e32 v5, 16, v5
	v_add3_u32 v6, v20, v6, s44
	v_and_or_b32 v5, v6, s45, v5
	v_or_b32_e32 v6, s18, v81
	v_lshlrev_b32_e32 v22, 12, v6
	v_mov_b32_e32 v23, v67
	v_lshl_add_u64 v[22:23], v[0:1], 0, v[22:23]
	global_store_dwordx4 v[22:23], v[2:5], off
	v_bfe_u32 v6, v21, 16, 1
	v_add3_u32 v6, v21, v6, s44
	v_bfe_u32 v2, v9, 16, 1
	v_add3_u32 v2, v9, v2, s44
	v_bfe_u32 v3, v7, 16, 1
	v_lshrrev_b32_e32 v2, 16, v2
	v_add3_u32 v3, v7, v3, s44
	v_and_or_b32 v2, v3, s45, v2
	v_bfe_u32 v3, v11, 16, 1
	v_add3_u32 v3, v11, v3, s44
	v_bfe_u32 v4, v13, 16, 1
	v_lshrrev_b32_e32 v3, 16, v3
	v_add3_u32 v4, v13, v4, s44
	v_and_or_b32 v3, v4, s45, v3
	v_bfe_u32 v4, v15, 16, 1
	v_add3_u32 v4, v15, v4, s44
	v_bfe_u32 v5, v17, 16, 1
	v_lshrrev_b32_e32 v4, 16, v4
	v_add3_u32 v5, v17, v5, s44
	v_and_or_b32 v4, v5, s45, v4
	v_bfe_u32 v5, v19, 16, 1
	v_add3_u32 v5, v19, v5, s44
	v_lshrrev_b32_e32 v5, 16, v5
	v_and_or_b32 v5, v6, s45, v5
	v_or_b32_e32 v6, s18, v82
	v_lshlrev_b32_e32 v6, 12, v6
	v_mov_b32_e32 v7, v67
	ds_read2_b32 v[8:9], v79 offset0:32 offset1:40
	v_lshl_add_u64 v[6:7], v[0:1], 0, v[6:7]
	global_store_dwordx4 v[6:7], v[2:5], off
	ds_read2_b32 v[6:7], v79 offset0:97 offset1:105
	ds_read2_b32 v[10:11], v79 offset0:162 offset1:170
	ds_read2_b32 v[12:13], v79 offset0:227 offset1:235
	s_waitcnt lgkmcnt(3)
	v_bfe_u32 v2, v8, 16, 1
	v_add3_u32 v2, v8, v2, s44
	s_waitcnt lgkmcnt(2)
	v_bfe_u32 v3, v6, 16, 1
	ds_read2_b32 v[14:15], v117 offset0:36 offset1:44
	v_lshrrev_b32_e32 v2, 16, v2
	v_add3_u32 v3, v6, v3, s44
	ds_read2_b32 v[16:17], v117 offset0:101 offset1:109
	v_and_or_b32 v2, v3, s45, v2
	s_waitcnt lgkmcnt(3)
	v_bfe_u32 v3, v10, 16, 1
	v_add3_u32 v3, v10, v3, s44
	s_waitcnt lgkmcnt(2)
	v_bfe_u32 v4, v12, 16, 1
	ds_read2_b32 v[18:19], v117 offset0:166 offset1:174
	v_lshrrev_b32_e32 v3, 16, v3
	v_add3_u32 v4, v12, v4, s44
	ds_read2_b32 v[20:21], v117 offset0:231 offset1:239
	v_and_or_b32 v3, v4, s45, v3
	s_waitcnt lgkmcnt(3)
	v_bfe_u32 v4, v14, 16, 1
	v_add3_u32 v4, v14, v4, s44
	s_waitcnt lgkmcnt(2)
	v_bfe_u32 v5, v16, 16, 1
	v_lshrrev_b32_e32 v4, 16, v4
	v_add3_u32 v5, v16, v5, s44
	v_and_or_b32 v4, v5, s45, v4
	s_waitcnt lgkmcnt(1)
	v_bfe_u32 v5, v18, 16, 1
	v_add3_u32 v5, v18, v5, s44
	s_waitcnt lgkmcnt(0)
	v_bfe_u32 v6, v20, 16, 1
	v_lshrrev_b32_e32 v5, 16, v5
	v_add3_u32 v6, v20, v6, s44
	v_and_or_b32 v5, v6, s45, v5
	v_or_b32_e32 v6, s18, v83
	v_lshlrev_b32_e32 v22, 12, v6
	v_mov_b32_e32 v23, v67
	v_lshl_add_u64 v[22:23], v[0:1], 0, v[22:23]
	global_store_dwordx4 v[22:23], v[2:5], off
	v_bfe_u32 v6, v21, 16, 1
	v_add3_u32 v6, v21, v6, s44
	v_bfe_u32 v2, v9, 16, 1
	v_add3_u32 v2, v9, v2, s44
	v_bfe_u32 v3, v7, 16, 1
	v_lshrrev_b32_e32 v2, 16, v2
	v_add3_u32 v3, v7, v3, s44
	v_and_or_b32 v2, v3, s45, v2
	v_bfe_u32 v3, v11, 16, 1
	v_add3_u32 v3, v11, v3, s44
	v_bfe_u32 v4, v13, 16, 1
	v_lshrrev_b32_e32 v3, 16, v3
	v_add3_u32 v4, v13, v4, s44
	v_and_or_b32 v3, v4, s45, v3
	v_bfe_u32 v4, v15, 16, 1
	v_add3_u32 v4, v15, v4, s44
	v_bfe_u32 v5, v17, 16, 1
	v_lshrrev_b32_e32 v4, 16, v4
	v_add3_u32 v5, v17, v5, s44
	v_and_or_b32 v4, v5, s45, v4
	v_bfe_u32 v5, v19, 16, 1
	v_add3_u32 v5, v19, v5, s44
	v_lshrrev_b32_e32 v5, 16, v5
	v_and_or_b32 v5, v6, s45, v5
	v_or_b32_e32 v6, s18, v84
	v_lshlrev_b32_e32 v6, 12, v6
	v_mov_b32_e32 v7, v67
	ds_read2_b32 v[8:9], v79 offset0:48 offset1:56
	v_lshl_add_u64 v[6:7], v[0:1], 0, v[6:7]
	global_store_dwordx4 v[6:7], v[2:5], off
	ds_read2_b32 v[6:7], v79 offset0:113 offset1:121
	ds_read2_b32 v[10:11], v79 offset0:178 offset1:186
	ds_read2_b32 v[12:13], v79 offset0:243 offset1:251
	s_waitcnt lgkmcnt(3)
	v_bfe_u32 v2, v8, 16, 1
	v_add3_u32 v2, v8, v2, s44
	s_waitcnt lgkmcnt(2)
	v_bfe_u32 v3, v6, 16, 1
	ds_read2_b32 v[14:15], v117 offset0:52 offset1:60
	v_lshrrev_b32_e32 v2, 16, v2
	v_add3_u32 v3, v6, v3, s44
	ds_read2_b32 v[16:17], v117 offset0:117 offset1:125
	v_and_or_b32 v2, v3, s45, v2
	s_waitcnt lgkmcnt(3)
	v_bfe_u32 v3, v10, 16, 1
	v_add3_u32 v3, v10, v3, s44
	s_waitcnt lgkmcnt(2)
	v_bfe_u32 v4, v12, 16, 1
	ds_read2_b32 v[18:19], v117 offset0:182 offset1:190
	v_lshrrev_b32_e32 v3, 16, v3
	v_add3_u32 v4, v12, v4, s44
	ds_read2_b32 v[20:21], v117 offset0:247 offset1:255
	v_and_or_b32 v3, v4, s45, v3
	s_waitcnt lgkmcnt(3)
	v_bfe_u32 v4, v14, 16, 1
	v_add3_u32 v4, v14, v4, s44
	s_waitcnt lgkmcnt(2)
	v_bfe_u32 v5, v16, 16, 1
	v_lshrrev_b32_e32 v4, 16, v4
	v_add3_u32 v5, v16, v5, s44
	v_and_or_b32 v4, v5, s45, v4
	s_waitcnt lgkmcnt(1)
	v_bfe_u32 v5, v18, 16, 1
	v_add3_u32 v5, v18, v5, s44
	s_waitcnt lgkmcnt(0)
	v_bfe_u32 v6, v20, 16, 1
	v_lshrrev_b32_e32 v5, 16, v5
	v_add3_u32 v6, v20, v6, s44
	v_and_or_b32 v5, v6, s45, v5
	v_or_b32_e32 v6, s18, v85
	v_lshlrev_b32_e32 v22, 12, v6
	v_mov_b32_e32 v23, v67
	v_lshl_add_u64 v[22:23], v[0:1], 0, v[22:23]
	global_store_dwordx4 v[22:23], v[2:5], off
	v_bfe_u32 v6, v21, 16, 1
	v_add3_u32 v6, v21, v6, s44
	v_bfe_u32 v2, v9, 16, 1
	v_add3_u32 v2, v9, v2, s44
	v_bfe_u32 v3, v7, 16, 1
	v_lshrrev_b32_e32 v2, 16, v2
	v_add3_u32 v3, v7, v3, s44
	v_and_or_b32 v2, v3, s45, v2
	v_bfe_u32 v3, v11, 16, 1
	v_add3_u32 v3, v11, v3, s44
	v_bfe_u32 v4, v13, 16, 1
	v_lshrrev_b32_e32 v3, 16, v3
	v_add3_u32 v4, v13, v4, s44
	v_and_or_b32 v3, v4, s45, v3
	v_bfe_u32 v4, v15, 16, 1
	v_add3_u32 v4, v15, v4, s44
	v_bfe_u32 v5, v17, 16, 1
	v_lshrrev_b32_e32 v4, 16, v4
	v_add3_u32 v5, v17, v5, s44
	v_and_or_b32 v4, v5, s45, v4
	v_bfe_u32 v5, v19, 16, 1
	v_add3_u32 v5, v19, v5, s44
	v_lshrrev_b32_e32 v5, 16, v5
	v_and_or_b32 v5, v6, s45, v5
	v_or_b32_e32 v6, s18, v86
	v_lshlrev_b32_e32 v6, 12, v6
	v_mov_b32_e32 v7, v67
	v_lshl_add_u64 v[0:1], v[0:1], 0, v[6:7]
	global_store_dwordx4 v[0:1], v[2:5], off
	s_waitcnt lgkmcnt(0)

.LBB0_47:
	s_load_dwordx2 s[48:49], s[20:21], 0x18
	s_ashr_i32 s18, s22, 11
	s_ashr_i32 s19, s18, 31
	s_lshl_b64 s[50:51], s[18:19], 25
	v_mov_b32_e32 v43, v67
	s_waitcnt lgkmcnt(0)
	s_add_u32 s23, s48, s50
	s_addc_u32 s48, s49, s51
	s_and_b32 s4, s22, 0x7c0
	s_lshl_b32 s22, s22, 6
	s_and_b32 s47, s22, 0xfc0
	s_lshl_b32 s22, s47, 2
	s_add_u32 s22, s23, s22
	v_or_b32_e32 v118, s4, v76
	s_addc_u32 s23, s48, 0
	v_lshl_add_u64 v[40:41], s[22:23], 0, v[66:67]
	v_lshlrev_b32_e32 v42, 14, v118
	v_lshl_add_u64 v[0:1], v[40:41], 0, v[42:43]
	v_or_b32_e32 v2, 0x10000, v42
	v_mov_b32_e32 v3, v67
	v_or_b32_e32 v8, 0x20000, v42
	v_mov_b32_e32 v9, v67
	v_or_b32_e32 v10, 0x30000, v42
	v_mov_b32_e32 v11, v67
	v_or_b32_e32 v16, 0x40000, v42
	v_mov_b32_e32 v17, v67
	v_or_b32_e32 v18, 0x50000, v42
	v_mov_b32_e32 v19, v67
	v_or_b32_e32 v24, 0x60000, v42
	v_mov_b32_e32 v25, v67
	v_or_b32_e32 v26, 0x70000, v42
	v_mov_b32_e32 v27, v67
	v_or_b32_e32 v32, 0x80000, v42
	v_mov_b32_e32 v33, v67
	v_or_b32_e32 v34, 0x90000, v42
	v_mov_b32_e32 v35, v67
	v_or_b32_e32 v44, 0xa0000, v42
	v_mov_b32_e32 v45, v67
	v_or_b32_e32 v46, 0xb0000, v42
	v_mov_b32_e32 v47, v67
	v_or_b32_e32 v48, 0xc0000, v42
	v_mov_b32_e32 v49, v67
	v_or_b32_e32 v50, 0xd0000, v42
	v_mov_b32_e32 v51, v67
	v_or_b32_e32 v52, 0xe0000, v42
	v_mov_b32_e32 v53, v67
	v_or_b32_e32 v42, 0xf0000, v42
	v_lshl_add_u64 v[2:3], v[40:41], 0, v[2:3]
	v_lshl_add_u64 v[8:9], v[40:41], 0, v[8:9]
	v_lshl_add_u64 v[10:11], v[40:41], 0, v[10:11]
	v_lshl_add_u64 v[16:17], v[40:41], 0, v[16:17]
	v_lshl_add_u64 v[18:19], v[40:41], 0, v[18:19]
	v_lshl_add_u64 v[24:25], v[40:41], 0, v[24:25]
	v_lshl_add_u64 v[26:27], v[40:41], 0, v[26:27]
	v_lshl_add_u64 v[32:33], v[40:41], 0, v[32:33]
	v_lshl_add_u64 v[34:35], v[40:41], 0, v[34:35]
	v_lshl_add_u64 v[44:45], v[40:41], 0, v[44:45]
	v_lshl_add_u64 v[46:47], v[40:41], 0, v[46:47]
	v_lshl_add_u64 v[48:49], v[40:41], 0, v[48:49]
	v_lshl_add_u64 v[50:51], v[40:41], 0, v[50:51]
	v_lshl_add_u64 v[120:121], v[40:41], 0, v[52:53]
	v_lshl_add_u64 v[40:41], v[40:41], 0, v[42:43]
	global_load_dwordx4 v[4:7], v[0:1], off nt
	s_nop 0
	global_load_dwordx4 v[0:3], v[2:3], off nt
	s_nop 0
	global_load_dwordx4 v[12:15], v[8:9], off nt
	s_nop 0
	global_load_dwordx4 v[8:11], v[10:11], off nt
	s_nop 0
	global_load_dwordx4 v[20:23], v[16:17], off nt
	s_nop 0
	global_load_dwordx4 v[16:19], v[18:19], off nt
	s_nop 0
	global_load_dwordx4 v[28:31], v[24:25], off nt
	s_nop 0
	global_load_dwordx4 v[24:27], v[26:27], off nt
	s_nop 0
	global_load_dwordx4 v[36:39], v[32:33], off nt
	s_nop 0
	global_load_dwordx4 v[32:35], v[34:35], off nt
	s_nop 0
	global_load_dwordx4 v[60:63], v[44:45], off nt
	global_load_dwordx4 v[56:59], v[46:47], off nt
	global_load_dwordx4 v[52:55], v[48:49], off nt
	s_nop 0
	global_load_dwordx4 v[48:51], v[50:51], off nt
	s_nop 0
	global_load_dwordx4 v[44:47], v[120:121], off nt
	s_nop 0
	global_load_dwordx4 v[40:43], v[40:41], off nt
	s_andn2_b64 vcc, exec, s[16:17]
	s_cbranch_vccnz .LBB0_25
	s_mul_i32 s22, s18, 0x1800
	s_ashr_i32 s23, s22, 31
	s_lshl_b64 s[22:23], s[22:23], 2
	s_add_u32 s22, s6, s22
	s_addc_u32 s23, s7, s23
	v_lshlrev_b32_e32 v119, 2, v118
	global_load_dword v160, v119, s[22:23]
	global_load_dword v161, v119, s[22:23] offset:16
	global_load_dword v162, v119, s[22:23] offset:32
	global_load_dword v163, v119, s[22:23] offset:48
	global_load_dword v164, v119, s[22:23] offset:64
	global_load_dword v165, v119, s[22:23] offset:80
	global_load_dword v166, v119, s[22:23] offset:96
	global_load_dword v167, v119, s[22:23] offset:112
	global_load_dword v168, v119, s[22:23] offset:128
	global_load_dword v169, v119, s[22:23] offset:144
	global_load_dword v170, v119, s[22:23] offset:160
	global_load_dword v171, v119, s[22:23] offset:176
	global_load_dword v172, v119, s[22:23] offset:192
	global_load_dword v173, v119, s[22:23] offset:208
	global_load_dword v174, v119, s[22:23] offset:224
	global_load_dword v175, v119, s[22:23] offset:240
	s_waitcnt vmcnt(0)
	v_mov_b32_e32 v118, v160
	s_waitcnt vmcnt(0)
	v_pk_mul_f32 v[6:7], v[6:7], v[118:119] op_sel_hi:[1,0]
	v_pk_mul_f32 v[4:5], v[4:5], v[118:119] op_sel_hi:[1,0]
	v_mov_b32_e32 v118, v161
	s_waitcnt vmcnt(0)
	v_pk_mul_f32 v[2:3], v[2:3], v[118:119] op_sel_hi:[1,0]
	v_pk_mul_f32 v[0:1], v[0:1], v[118:119] op_sel_hi:[1,0]
	v_mov_b32_e32 v118, v162
	s_waitcnt vmcnt(0)
	v_pk_mul_f32 v[14:15], v[14:15], v[118:119] op_sel_hi:[1,0]
	v_pk_mul_f32 v[12:13], v[12:13], v[118:119] op_sel_hi:[1,0]
	v_mov_b32_e32 v118, v163
	s_waitcnt vmcnt(0)
	v_pk_mul_f32 v[10:11], v[10:11], v[118:119] op_sel_hi:[1,0]
	v_pk_mul_f32 v[8:9], v[8:9], v[118:119] op_sel_hi:[1,0]
	v_mov_b32_e32 v118, v164
	s_waitcnt vmcnt(0)
	v_pk_mul_f32 v[22:23], v[22:23], v[118:119] op_sel_hi:[1,0]
	v_pk_mul_f32 v[20:21], v[20:21], v[118:119] op_sel_hi:[1,0]
	v_mov_b32_e32 v118, v165
	s_waitcnt vmcnt(0)
	v_pk_mul_f32 v[18:19], v[18:19], v[118:119] op_sel_hi:[1,0]
	v_pk_mul_f32 v[16:17], v[16:17], v[118:119] op_sel_hi:[1,0]
	v_mov_b32_e32 v118, v166
	s_waitcnt vmcnt(0)
	v_pk_mul_f32 v[30:31], v[30:31], v[118:119] op_sel_hi:[1,0]
	v_pk_mul_f32 v[28:29], v[28:29], v[118:119] op_sel_hi:[1,0]
	v_mov_b32_e32 v118, v167
	s_waitcnt vmcnt(0)
	v_pk_mul_f32 v[26:27], v[26:27], v[118:119] op_sel_hi:[1,0]
	v_pk_mul_f32 v[24:25], v[24:25], v[118:119] op_sel_hi:[1,0]
	v_mov_b32_e32 v118, v168
	s_waitcnt vmcnt(0)
	v_pk_mul_f32 v[38:39], v[38:39], v[118:119] op_sel_hi:[1,0]
	v_pk_mul_f32 v[36:37], v[36:37], v[118:119] op_sel_hi:[1,0]
	v_mov_b32_e32 v118, v169
	s_waitcnt vmcnt(0)
	v_pk_mul_f32 v[34:35], v[34:35], v[118:119] op_sel_hi:[1,0]
	v_pk_mul_f32 v[32:33], v[32:33], v[118:119] op_sel_hi:[1,0]
	v_mov_b32_e32 v118, v170
	s_waitcnt vmcnt(0)
	v_pk_mul_f32 v[62:63], v[62:63], v[118:119] op_sel_hi:[1,0]
	v_pk_mul_f32 v[60:61], v[60:61], v[118:119] op_sel_hi:[1,0]
	v_mov_b32_e32 v118, v171
	s_waitcnt vmcnt(0)
	v_pk_mul_f32 v[58:59], v[58:59], v[118:119] op_sel_hi:[1,0]
	v_pk_mul_f32 v[56:57], v[56:57], v[118:119] op_sel_hi:[1,0]
	v_mov_b32_e32 v118, v172
	s_waitcnt vmcnt(0)
	v_pk_mul_f32 v[54:55], v[54:55], v[118:119] op_sel_hi:[1,0]
	v_pk_mul_f32 v[52:53], v[52:53], v[118:119] op_sel_hi:[1,0]
	v_mov_b32_e32 v118, v173
	s_waitcnt vmcnt(0)
	v_pk_mul_f32 v[50:51], v[50:51], v[118:119] op_sel_hi:[1,0]
	v_pk_mul_f32 v[48:49], v[48:49], v[118:119] op_sel_hi:[1,0]
	v_mov_b32_e32 v118, v174
	s_waitcnt vmcnt(0)
	v_pk_mul_f32 v[46:47], v[46:47], v[118:119] op_sel_hi:[1,0]
	v_pk_mul_f32 v[44:45], v[44:45], v[118:119] op_sel_hi:[1,0]
	v_mov_b32_e32 v118, v175
	s_waitcnt vmcnt(0)
	v_pk_mul_f32 v[42:43], v[42:43], v[118:119] op_sel_hi:[1,0]
	v_pk_mul_f32 v[40:41], v[40:41], v[118:119] op_sel_hi:[1,0]
	s_branch .LBB0_25

.LBB0_57:
	v_add_co_u32_e32 v24, vcc, 0xfffff000, v4
	v_lshl_add_u64 v[6:7], s[14:15], 0, v[2:3]
	s_nop 0
	v_addc_co_u32_e32 v25, vcc, -1, v5, vcc
	s_waitcnt lgkmcnt(0)
	global_load_dwordx4 v[16:19], v[24:25], off offset:-3072 nt
	v_add_co_u32_e32 v6, vcc, s13, v6
	s_waitcnt vmcnt(0)
	v_and_b32_sdwa v21, v19, v14 dst_sel:DWORD dst_unused:UNUSED_PAD src0_sel:WORD_1 src1_sel:DWORD
	v_and_b32_sdwa v22, v17, v14 dst_sel:DWORD dst_unused:UNUSED_PAD src0_sel:WORD_1 src1_sel:DWORD
	v_and_b32_sdwa v15, v18, v14 dst_sel:DWORD dst_unused:UNUSED_PAD src0_sel:WORD_1 src1_sel:DWORD
	v_and_b32_sdwa v20, v16, v14 dst_sel:DWORD dst_unused:UNUSED_PAD src0_sel:WORD_1 src1_sel:DWORD
	v_add3_u32 v21, v19, v21, s1
	v_add3_u32 v22, v17, v22, s1
	v_add3_u32 v20, v16, v20, s1
	v_add3_u32 v15, v18, v15, s1
	v_and_b32_e32 v21, 0xffff0000, v21
	v_and_b32_e32 v22, 0xffff0000, v22
	v_addc_co_u32_e32 v7, vcc, 0, v7, vcc
	v_or_b32_sdwa v21, v21, v15 dst_sel:DWORD dst_unused:UNUSED_PAD src0_sel:DWORD src1_sel:WORD_1
	v_or_b32_sdwa v20, v22, v20 dst_sel:DWORD dst_unused:UNUSED_PAD src0_sel:DWORD src1_sel:WORD_1
	global_store_dwordx2 v[6:7], v[20:21], off
	global_load_dwordx4 v[20:23], v[24:25], off offset:-2048 nt
	s_waitcnt vmcnt(0)
	v_and_b32_sdwa v27, v23, v14 dst_sel:DWORD dst_unused:UNUSED_PAD src0_sel:WORD_1 src1_sel:DWORD
	v_and_b32_sdwa v28, v21, v14 dst_sel:DWORD dst_unused:UNUSED_PAD src0_sel:WORD_1 src1_sel:DWORD
	v_and_b32_sdwa v15, v22, v14 dst_sel:DWORD dst_unused:UNUSED_PAD src0_sel:WORD_1 src1_sel:DWORD
	v_and_b32_sdwa v26, v20, v14 dst_sel:DWORD dst_unused:UNUSED_PAD src0_sel:WORD_1 src1_sel:DWORD
	v_add3_u32 v27, v23, v27, s1
	v_add3_u32 v28, v21, v28, s1
	v_add3_u32 v26, v20, v26, s1
	v_add3_u32 v15, v22, v15, s1
	v_and_b32_e32 v27, 0xffff0000, v27
	v_and_b32_e32 v28, 0xffff0000, v28
	v_or_b32_sdwa v27, v27, v15 dst_sel:DWORD dst_unused:UNUSED_PAD src0_sel:DWORD src1_sel:WORD_1
	v_or_b32_sdwa v26, v28, v26 dst_sel:DWORD dst_unused:UNUSED_PAD src0_sel:DWORD src1_sel:WORD_1
	global_store_dwordx2 v[6:7], v[26:27], off offset:512
	global_load_dwordx4 v[24:27], v[24:25], off offset:-1024 nt
	s_waitcnt vmcnt(0)
	v_and_b32_sdwa v29, v27, v14 dst_sel:DWORD dst_unused:UNUSED_PAD src0_sel:WORD_1 src1_sel:DWORD
	v_and_b32_sdwa v30, v25, v14 dst_sel:DWORD dst_unused:UNUSED_PAD src0_sel:WORD_1 src1_sel:DWORD
	v_and_b32_sdwa v15, v26, v14 dst_sel:DWORD dst_unused:UNUSED_PAD src0_sel:WORD_1 src1_sel:DWORD
	v_and_b32_sdwa v28, v24, v14 dst_sel:DWORD dst_unused:UNUSED_PAD src0_sel:WORD_1 src1_sel:DWORD
	v_add3_u32 v29, v27, v29, s1
	v_add3_u32 v30, v25, v30, s1
	v_add3_u32 v28, v24, v28, s1
	v_add3_u32 v15, v26, v15, s1
	v_and_b32_e32 v29, 0xffff0000, v29
	v_and_b32_e32 v30, 0xffff0000, v30
	v_or_b32_sdwa v29, v29, v15 dst_sel:DWORD dst_unused:UNUSED_PAD src0_sel:DWORD src1_sel:WORD_1
	v_or_b32_sdwa v28, v30, v28 dst_sel:DWORD dst_unused:UNUSED_PAD src0_sel:DWORD src1_sel:WORD_1
	global_store_dwordx2 v[6:7], v[28:29], off offset:1024
	global_load_dwordx4 v[28:31], v[4:5], off offset:-4096 nt
	s_waitcnt vmcnt(0)
	v_and_b32_sdwa v33, v31, v14 dst_sel:DWORD dst_unused:UNUSED_PAD src0_sel:WORD_1 src1_sel:DWORD
	v_and_b32_sdwa v34, v29, v14 dst_sel:DWORD dst_unused:UNUSED_PAD src0_sel:WORD_1 src1_sel:DWORD
	v_and_b32_sdwa v15, v30, v14 dst_sel:DWORD dst_unused:UNUSED_PAD src0_sel:WORD_1 src1_sel:DWORD
	v_and_b32_sdwa v32, v28, v14 dst_sel:DWORD dst_unused:UNUSED_PAD src0_sel:WORD_1 src1_sel:DWORD
	v_add3_u32 v33, v31, v33, s1
	v_add3_u32 v34, v29, v34, s1
	v_add3_u32 v32, v28, v32, s1
	v_add3_u32 v15, v30, v15, s1
	v_and_b32_e32 v33, 0xffff0000, v33
	v_and_b32_e32 v34, 0xffff0000, v34
	v_or_b32_sdwa v33, v33, v15 dst_sel:DWORD dst_unused:UNUSED_PAD src0_sel:DWORD src1_sel:WORD_1
	v_or_b32_sdwa v32, v34, v32 dst_sel:DWORD dst_unused:UNUSED_PAD src0_sel:DWORD src1_sel:WORD_1
	global_store_dwordx2 v[6:7], v[32:33], off offset:1536
	global_load_dwordx4 v[32:35], v[4:5], off offset:-3072 nt
	s_waitcnt vmcnt(0)
	v_and_b32_sdwa v37, v35, v14 dst_sel:DWORD dst_unused:UNUSED_PAD src0_sel:WORD_1 src1_sel:DWORD
	v_and_b32_sdwa v38, v33, v14 dst_sel:DWORD dst_unused:UNUSED_PAD src0_sel:WORD_1 src1_sel:DWORD
	v_and_b32_sdwa v15, v34, v14 dst_sel:DWORD dst_unused:UNUSED_PAD src0_sel:WORD_1 src1_sel:DWORD
	v_and_b32_sdwa v36, v32, v14 dst_sel:DWORD dst_unused:UNUSED_PAD src0_sel:WORD_1 src1_sel:DWORD
	v_add3_u32 v37, v35, v37, s1
	v_add3_u32 v38, v33, v38, s1
	v_add3_u32 v36, v32, v36, s1
	v_add3_u32 v15, v34, v15, s1
	v_and_b32_e32 v37, 0xffff0000, v37
	v_and_b32_e32 v38, 0xffff0000, v38
	v_or_b32_sdwa v37, v37, v15 dst_sel:DWORD dst_unused:UNUSED_PAD src0_sel:DWORD src1_sel:WORD_1
	v_or_b32_sdwa v36, v38, v36 dst_sel:DWORD dst_unused:UNUSED_PAD src0_sel:DWORD src1_sel:WORD_1
	global_store_dwordx2 v[6:7], v[36:37], off offset:2048
	global_load_dwordx4 v[36:39], v[4:5], off offset:-2048 nt
	s_waitcnt vmcnt(0)
	v_and_b32_sdwa v41, v39, v14 dst_sel:DWORD dst_unused:UNUSED_PAD src0_sel:WORD_1 src1_sel:DWORD
	v_and_b32_sdwa v42, v37, v14 dst_sel:DWORD dst_unused:UNUSED_PAD src0_sel:WORD_1 src1_sel:DWORD
	v_and_b32_sdwa v15, v38, v14 dst_sel:DWORD dst_unused:UNUSED_PAD src0_sel:WORD_1 src1_sel:DWORD
	v_and_b32_sdwa v40, v36, v14 dst_sel:DWORD dst_unused:UNUSED_PAD src0_sel:WORD_1 src1_sel:DWORD
	v_add3_u32 v41, v39, v41, s1
	v_add3_u32 v42, v37, v42, s1
	v_add3_u32 v40, v36, v40, s1
	v_add3_u32 v15, v38, v15, s1
	v_and_b32_e32 v41, 0xffff0000, v41
	v_and_b32_e32 v42, 0xffff0000, v42
	v_or_b32_sdwa v41, v41, v15 dst_sel:DWORD dst_unused:UNUSED_PAD src0_sel:DWORD src1_sel:WORD_1
	v_or_b32_sdwa v40, v42, v40 dst_sel:DWORD dst_unused:UNUSED_PAD src0_sel:DWORD src1_sel:WORD_1
	global_store_dwordx2 v[6:7], v[40:41], off offset:2560
	global_load_dwordx4 v[40:43], v[4:5], off offset:-1024 nt
	s_waitcnt vmcnt(0)
	v_and_b32_sdwa v45, v43, v14 dst_sel:DWORD dst_unused:UNUSED_PAD src0_sel:WORD_1 src1_sel:DWORD
	v_and_b32_sdwa v46, v41, v14 dst_sel:DWORD dst_unused:UNUSED_PAD src0_sel:WORD_1 src1_sel:DWORD
	v_and_b32_sdwa v15, v42, v14 dst_sel:DWORD dst_unused:UNUSED_PAD src0_sel:WORD_1 src1_sel:DWORD
	v_and_b32_sdwa v44, v40, v14 dst_sel:DWORD dst_unused:UNUSED_PAD src0_sel:WORD_1 src1_sel:DWORD
	v_add3_u32 v45, v43, v45, s1
	v_add3_u32 v46, v41, v46, s1
	v_add3_u32 v44, v40, v44, s1
	v_add3_u32 v15, v42, v15, s1
	v_and_b32_e32 v45, 0xffff0000, v45
	v_and_b32_e32 v46, 0xffff0000, v46
	v_or_b32_sdwa v45, v45, v15 dst_sel:DWORD dst_unused:UNUSED_PAD src0_sel:DWORD src1_sel:WORD_1
	v_or_b32_sdwa v44, v46, v44 dst_sel:DWORD dst_unused:UNUSED_PAD src0_sel:DWORD src1_sel:WORD_1
	global_store_dwordx2 v[6:7], v[44:45], off offset:3072
	global_load_dwordx4 v[44:47], v[4:5], off nt
	v_mul_f32_e32 v15, v17, v17
	v_mul_f32_e32 v17, v19, v19
	v_fmac_f32_e32 v15, v16, v16
	v_fmac_f32_e32 v17, v18, v18
	v_add_f32_e32 v15, v15, v17
	v_mul_f32_e32 v16, v21, v21
	v_mul_f32_e32 v17, v23, v23
	v_fmac_f32_e32 v16, v20, v20
	v_fmac_f32_e32 v17, v22, v22
	v_add_f32_e32 v16, v16, v17
	v_add_f32_e32 v15, v15, v16
	v_mul_f32_e32 v16, v25, v25
	v_mul_f32_e32 v17, v27, v27
	v_fmac_f32_e32 v16, v24, v24
	v_fmac_f32_e32 v17, v26, v26
	v_add_f32_e32 v16, v16, v17
	v_add_f32_e32 v15, v15, v16
	v_mul_f32_e32 v16, v29, v29
	v_mul_f32_e32 v17, v31, v31
	v_fmac_f32_e32 v16, v28, v28
	v_fmac_f32_e32 v17, v30, v30
	v_add_f32_e32 v16, v16, v17
	v_add_f32_e32 v15, v15, v16
	v_mul_f32_e32 v16, v33, v33
	v_mul_f32_e32 v17, v35, v35
	v_fmac_f32_e32 v16, v32, v32
	v_fmac_f32_e32 v17, v34, v34
	v_add_f32_e32 v16, v16, v17
	v_add_f32_e32 v15, v15, v16
	v_mul_f32_e32 v16, v37, v37
	v_mul_f32_e32 v17, v39, v39
	v_fmac_f32_e32 v16, v36, v36
	v_fmac_f32_e32 v17, v38, v38
	v_add_f32_e32 v16, v16, v17
	v_add_f32_e32 v15, v15, v16
	v_mul_f32_e32 v16, v41, v41
	v_mul_f32_e32 v17, v43, v43
	v_fmac_f32_e32 v16, v40, v40
	v_fmac_f32_e32 v17, v42, v42
	v_add_f32_e32 v16, v16, v17
	v_add_f32_e32 v15, v15, v16
	s_waitcnt vmcnt(0)
	v_mul_f32_e32 v16, v45, v45
	v_mul_f32_e32 v17, v47, v47
	v_fmac_f32_e32 v16, v44, v44
	v_fmac_f32_e32 v17, v46, v46
	v_add_f32_e32 v16, v16, v17
	v_add_f32_e32 v15, v15, v16
	ds_bpermute_b32 v16, v8, v15
	v_and_b32_sdwa v19, v47, v14 dst_sel:DWORD dst_unused:UNUSED_PAD src0_sel:WORD_1 src1_sel:DWORD
	v_and_b32_sdwa v20, v45, v14 dst_sel:DWORD dst_unused:UNUSED_PAD src0_sel:WORD_1 src1_sel:DWORD
	v_and_b32_sdwa v17, v46, v14 dst_sel:DWORD dst_unused:UNUSED_PAD src0_sel:WORD_1 src1_sel:DWORD
	v_and_b32_sdwa v18, v44, v14 dst_sel:DWORD dst_unused:UNUSED_PAD src0_sel:WORD_1 src1_sel:DWORD
	s_waitcnt lgkmcnt(0)
	v_add_f32_e32 v15, v15, v16
	ds_bpermute_b32 v16, v9, v15
	v_add3_u32 v19, v47, v19, s1
	v_add3_u32 v20, v45, v20, s1
	v_add3_u32 v18, v44, v18, s1
	v_add3_u32 v17, v46, v17, s1
	s_waitcnt lgkmcnt(0)
	v_add_f32_e32 v15, v15, v16
	ds_bpermute_b32 v16, v10, v15
	v_and_b32_e32 v19, 0xffff0000, v19
	v_and_b32_e32 v20, 0xffff0000, v20
	v_or_b32_sdwa v19, v19, v17 dst_sel:DWORD dst_unused:UNUSED_PAD src0_sel:DWORD src1_sel:WORD_1
	v_or_b32_sdwa v18, v20, v18 dst_sel:DWORD dst_unused:UNUSED_PAD src0_sel:DWORD src1_sel:WORD_1
	s_waitcnt lgkmcnt(0)
	v_add_f32_e32 v15, v15, v16
	ds_bpermute_b32 v16, v11, v15
	global_store_dwordx2 v[6:7], v[18:19], off offset:3584
	s_waitcnt lgkmcnt(0)
	v_add_f32_e32 v15, v15, v16
	ds_bpermute_b32 v16, v12, v15
	s_waitcnt lgkmcnt(0)
	v_add_f32_e32 v15, v15, v16
	ds_bpermute_b32 v16, v13, v15
	s_and_saveexec_b64 s[16:17], s[4:5]
	s_cbranch_execz .LBB0_56
	s_waitcnt lgkmcnt(0)
	v_add_f32_e32 v6, v15, v16
	v_cndmask_b32_e64 v15, 0, v6, s[6:7]
	v_lshl_add_u64 v[6:7], s[14:15], 0, v[0:1]
	global_store_dword v[6:7], v15, off
	s_branch .LBB0_56

.LBB0_62:
	s_or_b64 exec, exec, s[2:3]
	s_waitcnt vmcnt(0)
	v_cvt_f64_f32_e32 v[34:35], v0
	v_mul_f64 v[20:21], v[20:21], v[34:35]
	v_ldexp_f64 v[22:23], v[20:21], -6
	v_fma_f64 v[20:21], v[20:21], s[14:15], 1.0
	v_mul_f64 v[24:25], v[22:23], 0.5
	s_mov_b32 s18, s28
	v_mul_f64 v[26:27], v[22:23], v[24:25]
	v_fmac_f64_e32 v[20:21], v[22:23], v[24:25]
	v_mul_f64 v[24:25], v[22:23], s[18:19]
	v_mul_f64 v[28:29], v[24:25], v[26:27]
	v_fmac_f64_e32 v[20:21], v[24:25], v[26:27]
	v_ldexp_f64 v[24:25], v[22:23], -2
	v_mul_f64 v[26:27], v[24:25], v[28:29]
	v_fmac_f64_e32 v[20:21], v[24:25], v[28:29]
	v_mul_f64 v[24:25], v[22:23], s[34:35]
	v_mul_f64 v[28:29], v[24:25], v[26:27]
	v_fmac_f64_e32 v[20:21], v[24:25], v[26:27]
	v_mul_f64 v[24:25], v[22:23], s[28:29]
	v_mul_f64 v[26:27], v[24:25], v[28:29]
	v_fmac_f64_e32 v[20:21], v[24:25], v[28:29]
	v_mul_f64 v[24:25], v[22:23], s[36:37]
	v_mul_f64 v[28:29], v[24:25], v[26:27]
	v_fmac_f64_e32 v[20:21], v[24:25], v[26:27]
	v_ldexp_f64 v[24:25], v[22:23], -3
	v_mul_f64 v[26:27], v[24:25], v[28:29]
	v_fmac_f64_e32 v[20:21], v[24:25], v[28:29]
	v_mul_f64 v[24:25], v[22:23], s[38:39]
	v_mul_f64 v[28:29], v[24:25], v[26:27]
	v_fmac_f64_e32 v[20:21], v[24:25], v[26:27]
	v_mul_f64 v[24:25], v[22:23], s[40:41]
	v_mul_f64 v[26:27], v[24:25], v[28:29]
	v_fmac_f64_e32 v[20:21], v[24:25], v[28:29]
	v_mul_f64 v[24:25], v[22:23], s[42:43]
	v_mul_f64 v[28:29], v[24:25], v[26:27]
	v_fmac_f64_e32 v[20:21], v[24:25], v[26:27]
	v_mul_f64 v[24:25], v[22:23], s[44:45]
	v_mul_f64 v[26:27], v[24:25], v[28:29]
	v_fmac_f64_e32 v[20:21], v[24:25], v[28:29]
	v_mul_f64 v[24:25], v[22:23], s[46:47]
	v_mul_f64 v[28:29], v[24:25], v[26:27]
	v_fmac_f64_e32 v[20:21], v[24:25], v[26:27]
	v_mul_f64 v[22:23], v[22:23], s[48:49]
	v_fmac_f64_e32 v[20:21], v[22:23], v[28:29]
	v_mul_f64 v[20:21], v[20:21], v[20:21]
	v_mul_f64 v[20:21], v[20:21], v[20:21]
	v_mul_f64 v[20:21], v[20:21], v[20:21]
	v_mul_f64 v[20:21], v[20:21], v[20:21]
	v_mul_f64 v[20:21], v[20:21], v[20:21]
	v_mul_f64 v[36:37], v[20:21], v[20:21]
	v_mul_f64 v[20:21], v[36:37], v[16:17]
	v_mul_f64 v[38:39], v[36:37], v[18:19]
	v_ashrrev_i32_e32 v5, 31, v4
	v_lshl_add_u64 v[18:19], v[4:5], 2, s[22:23]
	v_cvt_f32_f64_e32 v23, v[38:39]
	v_cvt_f32_f64_e32 v22, v[20:21]
	global_store_dwordx2 v[18:19], v[22:23], off
	v_lshlrev_b64 v[18:19], 6, v[2:3]
	v_lshl_add_u64 v[40:41], s[10:11], 0, v[18:19]
	v_lshl_add_u64 v[42:43], s[16:17], 0, v[18:19]
	global_load_dwordx4 v[18:21], v[40:41], off nt
	global_load_dwordx4 v[22:25], v[42:43], off nt
	global_load_dwordx4 v[26:29], v[40:41], off offset:16 nt
	global_load_dwordx4 v[30:33], v[42:43], off offset:16 nt
	v_fma_f64 v[16:17], v[36:37], v[16:17], -1.0
	v_mul_f64 v[46:47], v[14:15], v[14:15]
	v_mul_f64 v[48:49], v[16:17], v[34:35]
	v_mul_f64 v[16:17], v[16:17], v[14:15]
	v_fmac_f64_e32 v[46:47], v[34:35], v[34:35]
	v_fmac_f64_e32 v[48:49], v[38:39], v[14:15]
	v_fma_f64 v[50:51], v[38:39], v[34:35], -v[16:17]
	global_load_dwordx4 v[14:17], v[40:41], off offset:48 nt
	global_load_dwordx4 v[34:37], v[40:41], off offset:32 nt
	s_nop 0
	global_load_dwordx4 v[38:41], v[42:43], off offset:48 nt
	s_nop 0
	global_load_dwordx4 v[42:45], v[42:43], off offset:32 nt
	v_div_scale_f64 v[52:53], s[2:3], v[46:47], v[46:47], v[48:49]
	v_div_scale_f64 v[56:57], s[2:3], v[46:47], v[46:47], v[50:51]
	v_rcp_f64_e32 v[60:61], v[52:53]
	v_rcp_f64_e32 v[62:63], v[56:57]
	v_div_scale_f64 v[54:55], vcc, v[48:49], v[46:47], v[48:49]
	v_fma_f64 v[64:65], -v[52:53], v[60:61], 1.0
	v_fma_f64 v[68:69], -v[56:57], v[62:63], 1.0
	v_fmac_f64_e32 v[60:61], v[60:61], v[64:65]
	v_fmac_f64_e32 v[62:63], v[62:63], v[68:69]
	v_fma_f64 v[64:65], -v[52:53], v[60:61], 1.0
	v_fma_f64 v[68:69], -v[56:57], v[62:63], 1.0
	v_fmac_f64_e32 v[60:61], v[60:61], v[64:65]
	v_div_scale_f64 v[58:59], s[2:3], v[50:51], v[46:47], v[50:51]
	v_fmac_f64_e32 v[62:63], v[62:63], v[68:69]
	v_mul_f64 v[64:65], v[54:55], v[60:61]
	v_mul_f64 v[68:69], v[58:59], v[62:63]
	v_fma_f64 v[52:53], -v[52:53], v[64:65], v[54:55]
	v_fma_f64 v[54:55], -v[56:57], v[68:69], v[58:59]
	v_div_fmas_f64 v[52:53], v[52:53], v[60:61], v[64:65]
	s_mov_b64 vcc, s[2:3]
	v_div_fixup_f64 v[48:49], v[52:53], v[46:47], v[48:49]
	v_div_fmas_f64 v[52:53], v[54:55], v[62:63], v[68:69]
	v_div_fixup_f64 v[46:47], v[52:53], v[46:47], v[50:51]
	s_add_i32 s0, s0, s12
	s_add_u32 s8, s8, s26
	s_addc_u32 s9, s9, s27
	v_add_u32_e32 v4, s89, v4
	v_add_u32_e32 v2, s90, v2
	s_cmpk_lt_i32 s0, 0x100
	s_waitcnt vmcnt(7)
	v_cvt_f64_f32_e32 v[50:51], v18
	s_waitcnt vmcnt(6)
	v_cvt_f64_f32_e32 v[52:53], v22
	v_cvt_f64_f32_e32 v[54:55], v19
	v_cvt_f64_f32_e32 v[22:23], v23
	v_mul_f64 v[18:19], v[46:47], v[52:53]
	v_mul_f64 v[56:57], v[46:47], v[22:23]
	v_fma_f64 v[18:19], v[48:49], v[50:51], -v[18:19]
	v_cvt_f32_f64_e32 v0, v[18:19]
	v_fma_f64 v[18:19], v[48:49], v[54:55], -v[56:57]
	v_cvt_f32_f64_e32 v3, v[18:19]
	v_bfe_u32 v5, v0, 16, 1
	v_add3_u32 v0, v0, v5, s1
	v_bfe_u32 v5, v3, 16, 1
	v_mul_f64 v[52:53], v[48:49], v[52:53]
	v_lshrrev_b32_e32 v0, 16, v0
	v_add3_u32 v3, v3, v5, s1
	v_fmac_f64_e32 v[52:53], v[46:47], v[50:51]
	v_mul_f64 v[22:23], v[48:49], v[22:23]
	v_and_or_b32 v18, v3, s13, v0
	v_cvt_f32_f64_e32 v0, v[52:53]
	v_fmac_f64_e32 v[22:23], v[46:47], v[54:55]
	v_cvt_f32_f64_e32 v3, v[22:23]
	v_bfe_u32 v5, v0, 16, 1
	v_cvt_f64_f32_e32 v[52:53], v24
	v_add3_u32 v0, v0, v5, s1
	v_bfe_u32 v5, v3, 16, 1
	v_cvt_f64_f32_e32 v[50:51], v20
	v_mul_f64 v[54:55], v[46:47], v[52:53]
	v_lshrrev_b32_e32 v0, 16, v0
	v_add3_u32 v3, v3, v5, s1
	v_cvt_f64_f32_e32 v[24:25], v25
	v_fma_f64 v[54:55], v[48:49], v[50:51], -v[54:55]
	v_and_or_b32 v22, v3, s13, v0
	v_cvt_f64_f32_e32 v[20:21], v21
	v_cvt_f32_f64_e32 v0, v[54:55]
	v_mul_f64 v[54:55], v[46:47], v[24:25]
	v_fma_f64 v[54:55], v[48:49], v[20:21], -v[54:55]
	v_cvt_f32_f64_e32 v3, v[54:55]
	v_bfe_u32 v5, v0, 16, 1
	v_add3_u32 v0, v0, v5, s1
	v_bfe_u32 v5, v3, 16, 1
	v_mul_f64 v[52:53], v[48:49], v[52:53]
	v_lshrrev_b32_e32 v0, 16, v0
	v_add3_u32 v3, v3, v5, s1
	v_fmac_f64_e32 v[52:53], v[46:47], v[50:51]
	v_mul_f64 v[24:25], v[48:49], v[24:25]
	v_and_or_b32 v19, v3, s13, v0
	v_cvt_f32_f64_e32 v0, v[52:53]
	v_fmac_f64_e32 v[24:25], v[46:47], v[20:21]
	v_cvt_f32_f64_e32 v3, v[24:25]
	v_bfe_u32 v5, v0, 16, 1
	s_waitcnt vmcnt(4)
	v_cvt_f64_f32_e32 v[50:51], v30
	v_add3_u32 v0, v0, v5, s1
	v_bfe_u32 v5, v3, 16, 1
	v_cvt_f64_f32_e32 v[24:25], v26
	v_mul_f64 v[20:21], v[46:47], v[50:51]
	v_lshrrev_b32_e32 v0, 16, v0
	v_add3_u32 v3, v3, v5, s1
	v_cvt_f64_f32_e32 v[30:31], v31
	v_fma_f64 v[20:21], v[48:49], v[24:25], -v[20:21]
	v_and_or_b32 v23, v3, s13, v0
	v_cvt_f64_f32_e32 v[26:27], v27
	v_cvt_f32_f64_e32 v0, v[20:21]
	v_mul_f64 v[20:21], v[46:47], v[30:31]
	v_fma_f64 v[20:21], v[48:49], v[26:27], -v[20:21]
	v_cvt_f32_f64_e32 v3, v[20:21]
	v_bfe_u32 v5, v0, 16, 1
	v_add3_u32 v0, v0, v5, s1
	v_bfe_u32 v5, v3, 16, 1
	v_mul_f64 v[50:51], v[48:49], v[50:51]
	v_lshrrev_b32_e32 v0, 16, v0
	v_add3_u32 v3, v3, v5, s1
	v_fmac_f64_e32 v[50:51], v[46:47], v[24:25]
	v_mul_f64 v[24:25], v[48:49], v[30:31]
	v_and_or_b32 v20, v3, s13, v0
	v_cvt_f32_f64_e32 v0, v[50:51]
	v_fmac_f64_e32 v[24:25], v[46:47], v[26:27]
	v_cvt_f32_f64_e32 v3, v[24:25]
	v_bfe_u32 v5, v0, 16, 1
	v_cvt_f64_f32_e32 v[30:31], v32
	v_add3_u32 v0, v0, v5, s1
	v_bfe_u32 v5, v3, 16, 1
	v_cvt_f64_f32_e32 v[26:27], v28
	v_mul_f64 v[50:51], v[46:47], v[30:31]
	v_lshrrev_b32_e32 v0, 16, v0
	v_add3_u32 v3, v3, v5, s1
	v_cvt_f64_f32_e32 v[32:33], v33
	v_fma_f64 v[50:51], v[48:49], v[26:27], -v[50:51]
	v_and_or_b32 v24, v3, s13, v0
	v_cvt_f64_f32_e32 v[28:29], v29
	v_cvt_f32_f64_e32 v0, v[50:51]
	v_mul_f64 v[50:51], v[46:47], v[32:33]
	v_fma_f64 v[50:51], v[48:49], v[28:29], -v[50:51]
	v_cvt_f32_f64_e32 v3, v[50:51]
	v_bfe_u32 v5, v0, 16, 1
	v_add3_u32 v0, v0, v5, s1
	v_bfe_u32 v5, v3, 16, 1
	v_mul_f64 v[30:31], v[48:49], v[30:31]
	v_lshrrev_b32_e32 v0, 16, v0
	v_add3_u32 v3, v3, v5, s1
	v_fmac_f64_e32 v[30:31], v[46:47], v[26:27]
	v_mul_f64 v[26:27], v[48:49], v[32:33]
	v_and_or_b32 v21, v3, s13, v0
	v_cvt_f32_f64_e32 v0, v[30:31]
	v_fmac_f64_e32 v[26:27], v[46:47], v[28:29]
	v_cvt_f32_f64_e32 v3, v[26:27]
	v_bfe_u32 v5, v0, 16, 1
	s_waitcnt vmcnt(0)
	v_cvt_f64_f32_e32 v[30:31], v42
	v_add3_u32 v0, v0, v5, s1
	v_bfe_u32 v5, v3, 16, 1
	v_cvt_f64_f32_e32 v[28:29], v34
	v_mul_f64 v[26:27], v[46:47], v[30:31]
	v_lshrrev_b32_e32 v0, 16, v0
	v_add3_u32 v3, v3, v5, s1
	v_cvt_f64_f32_e32 v[32:33], v35
	v_cvt_f64_f32_e32 v[34:35], v43
	v_fma_f64 v[26:27], v[48:49], v[28:29], -v[26:27]
	v_and_or_b32 v25, v3, s13, v0
	v_cvt_f32_f64_e32 v0, v[26:27]
	v_mul_f64 v[26:27], v[46:47], v[34:35]
	v_fma_f64 v[26:27], v[48:49], v[32:33], -v[26:27]
	v_cvt_f32_f64_e32 v3, v[26:27]
	v_bfe_u32 v5, v0, 16, 1
	v_add3_u32 v0, v0, v5, s1
	v_bfe_u32 v5, v3, 16, 1
	v_mul_f64 v[30:31], v[48:49], v[30:31]
	v_lshrrev_b32_e32 v0, 16, v0
	v_add3_u32 v3, v3, v5, s1
	v_fmac_f64_e32 v[30:31], v[46:47], v[28:29]
	v_mul_f64 v[28:29], v[48:49], v[34:35]
	v_and_or_b32 v26, v3, s13, v0
	v_cvt_f32_f64_e32 v0, v[30:31]
	v_fmac_f64_e32 v[28:29], v[46:47], v[32:33]
	v_cvt_f32_f64_e32 v3, v[28:29]
	v_bfe_u32 v5, v0, 16, 1
	v_cvt_f64_f32_e32 v[32:33], v44
	v_add3_u32 v0, v0, v5, s1
	v_bfe_u32 v5, v3, 16, 1
	v_cvt_f64_f32_e32 v[28:29], v36
	v_mul_f64 v[42:43], v[46:47], v[32:33]
	v_lshrrev_b32_e32 v0, 16, v0
	v_add3_u32 v3, v3, v5, s1
	v_cvt_f64_f32_e32 v[34:35], v37
	v_cvt_f64_f32_e32 v[36:37], v45
	v_fma_f64 v[42:43], v[48:49], v[28:29], -v[42:43]
	v_and_or_b32 v30, v3, s13, v0
	v_cvt_f32_f64_e32 v0, v[42:43]
	v_mul_f64 v[42:43], v[46:47], v[36:37]
	v_fma_f64 v[42:43], v[48:49], v[34:35], -v[42:43]
	v_cvt_f32_f64_e32 v3, v[42:43]
	v_bfe_u32 v5, v0, 16, 1
	v_add3_u32 v0, v0, v5, s1
	v_bfe_u32 v5, v3, 16, 1
	v_mul_f64 v[32:33], v[48:49], v[32:33]
	v_lshrrev_b32_e32 v0, 16, v0
	v_add3_u32 v3, v3, v5, s1
	v_fmac_f64_e32 v[32:33], v[46:47], v[28:29]
	v_mul_f64 v[28:29], v[48:49], v[36:37]
	v_and_or_b32 v27, v3, s13, v0
	v_cvt_f32_f64_e32 v0, v[32:33]
	v_fmac_f64_e32 v[28:29], v[46:47], v[34:35]
	v_cvt_f32_f64_e32 v3, v[28:29]
	v_bfe_u32 v5, v0, 16, 1
	v_cvt_f64_f32_e32 v[34:35], v38
	v_add3_u32 v0, v0, v5, s1
	v_bfe_u32 v5, v3, 16, 1
	v_cvt_f64_f32_e32 v[32:33], v14
	v_mul_f64 v[28:29], v[46:47], v[34:35]
	v_lshrrev_b32_e32 v0, 16, v0
	v_add3_u32 v3, v3, v5, s1
	v_cvt_f64_f32_e32 v[36:37], v39
	v_fma_f64 v[28:29], v[48:49], v[32:33], -v[28:29]
	v_and_or_b32 v31, v3, s13, v0
	v_cvt_f64_f32_e32 v[14:15], v15
	v_cvt_f32_f64_e32 v0, v[28:29]
	v_mul_f64 v[28:29], v[46:47], v[36:37]
	v_fma_f64 v[28:29], v[48:49], v[14:15], -v[28:29]
	v_cvt_f32_f64_e32 v3, v[28:29]
	v_bfe_u32 v5, v0, 16, 1
	v_add3_u32 v0, v0, v5, s1
	v_bfe_u32 v5, v3, 16, 1
	v_mul_f64 v[34:35], v[48:49], v[34:35]
	v_lshrrev_b32_e32 v0, 16, v0
	v_add3_u32 v3, v3, v5, s1
	v_fmac_f64_e32 v[34:35], v[46:47], v[32:33]
	v_mul_f64 v[32:33], v[48:49], v[36:37]
	v_and_or_b32 v28, v3, s13, v0
	v_cvt_f32_f64_e32 v0, v[34:35]
	v_fmac_f64_e32 v[32:33], v[46:47], v[14:15]
	v_cvt_f32_f64_e32 v3, v[32:33]
	v_bfe_u32 v5, v0, 16, 1
	v_cvt_f64_f32_e32 v[34:35], v40
	v_add3_u32 v0, v0, v5, s1
	v_bfe_u32 v5, v3, 16, 1
	v_cvt_f64_f32_e32 v[14:15], v16
	v_mul_f64 v[38:39], v[46:47], v[34:35]
	v_lshrrev_b32_e32 v0, 16, v0
	v_add3_u32 v3, v3, v5, s1
	v_cvt_f64_f32_e32 v[36:37], v41
	v_fma_f64 v[38:39], v[48:49], v[14:15], -v[38:39]
	v_and_or_b32 v32, v3, s13, v0
	v_cvt_f64_f32_e32 v[16:17], v17
	v_cvt_f32_f64_e32 v0, v[38:39]
	v_mul_f64 v[38:39], v[46:47], v[36:37]
	v_fma_f64 v[38:39], v[48:49], v[16:17], -v[38:39]
	v_cvt_f32_f64_e32 v3, v[38:39]
	v_bfe_u32 v5, v0, 16, 1
	v_add3_u32 v0, v0, v5, s1
	v_bfe_u32 v5, v3, 16, 1
	v_mul_f64 v[34:35], v[48:49], v[34:35]
	v_lshrrev_b32_e32 v0, 16, v0
	v_add3_u32 v3, v3, v5, s1
	v_fmac_f64_e32 v[34:35], v[46:47], v[14:15]
	v_mul_f64 v[14:15], v[48:49], v[36:37]
	v_and_or_b32 v29, v3, s13, v0
	v_cvt_f32_f64_e32 v0, v[34:35]
	v_fmac_f64_e32 v[14:15], v[46:47], v[16:17]
	v_cvt_f32_f64_e32 v3, v[14:15]
	v_bfe_u32 v5, v0, 16, 1
	v_lshl_add_u64 v[14:15], v[8:9], 0, s[20:21]
	v_add3_u32 v0, v0, v5, s1
	v_bfe_u32 v5, v3, 16, 1
	v_add_co_u32_e32 v14, vcc, s91, v14
	v_lshrrev_b32_e32 v0, 16, v0
	v_add3_u32 v3, v3, v5, s1
	v_addc_co_u32_e32 v15, vcc, 0, v15, vcc
	v_and_or_b32 v33, v3, s13, v0
	global_store_dwordx4 v[14:15], v[18:21], off
	global_store_dwordx4 v[14:15], v[26:29], off offset:16
	global_store_dwordx4 v[14:15], v[22:25], off offset:2048
	global_store_dwordx4 v[14:15], v[30:33], off offset:2064
	v_lshl_add_u64 v[16:17], v[12:13], 0, s[20:21]
	v_lshl_add_u64 v[14:15], v[10:11], 0, s[20:21]
	global_load_dword v0, v[16:17], off
	global_load_dword v3, v[14:15], off
	global_load_dword v5, v[16:17], off offset:256
	global_load_dword v20, v[14:15], off offset:256
	global_load_dword v21, v[16:17], off offset:512
	global_load_dword v22, v[14:15], off offset:512
	global_load_dword v23, v[16:17], off offset:768
	global_load_dword v24, v[14:15], off offset:768
	global_load_dword v25, v[16:17], off offset:1024
	global_load_dword v26, v[14:15], off offset:1024
	global_load_dword v27, v[16:17], off offset:1280
	global_load_dword v28, v[14:15], off offset:1280
	global_load_dword v29, v[16:17], off offset:1536
	global_load_dword v30, v[14:15], off offset:1536
	global_load_dword v31, v[16:17], off offset:1792
	global_load_dword v32, v[14:15], off offset:1792
	global_load_dword v33, v[16:17], off offset:2048
	global_load_dword v34, v[14:15], off offset:2048
	v_lshl_add_u64 v[8:9], v[8:9], 0, s[24:25]
	v_lshl_add_u64 v[10:11], v[10:11], 0, s[24:25]
	v_lshl_add_u64 v[12:13], v[12:13], 0, s[24:25]
	s_waitcnt vmcnt(17)
	v_xor_b32_e32 v0, 0x80000000, v0
	s_waitcnt vmcnt(16)
	v_bfe_u32 v18, v3, 16, 1
	v_add3_u32 v3, v3, v18, s1
	v_bfe_u32 v18, v0, 16, 1
	v_lshrrev_b32_e32 v3, 16, v3
	v_add3_u32 v0, v0, v18, s1
	v_and_or_b32 v0, v0, s13, v3
	v_lshl_add_u64 v[18:19], v[6:7], 0, s[20:21]
	global_load_dword v3, v[14:15], off offset:2304
	global_load_dword v35, v[16:17], off offset:2304
	v_add_co_u32_e32 v18, vcc, s92, v18
	v_lshl_add_u64 v[6:7], v[6:7], 0, s[24:25]
	s_nop 0
	v_addc_co_u32_e32 v19, vcc, 0, v19, vcc
	global_store_dword v[18:19], v0, off
	s_waitcnt vmcnt(18)
	v_xor_b32_e32 v0, 0x80000000, v5
	s_waitcnt vmcnt(17)
	v_bfe_u32 v5, v20, 16, 1
	v_add3_u32 v5, v20, v5, s1
	global_load_dword v20, v[16:17], off offset:2560
	global_load_dword v36, v[14:15], off offset:2560
	v_bfe_u32 v37, v0, 16, 1
	v_lshrrev_b32_e32 v5, 16, v5
	v_add3_u32 v0, v0, v37, s1
	v_and_or_b32 v0, v0, s13, v5
	global_store_dword v[18:19], v0, off offset:256
	s_waitcnt vmcnt(19)
	v_xor_b32_e32 v0, 0x80000000, v21
	s_waitcnt vmcnt(18)
	v_bfe_u32 v5, v22, 16, 1
	global_load_dword v21, v[16:17], off offset:2816
	global_load_dword v37, v[14:15], off offset:2816
	v_add3_u32 v5, v22, v5, s1
	v_bfe_u32 v22, v0, 16, 1
	v_lshrrev_b32_e32 v5, 16, v5
	v_add3_u32 v0, v0, v22, s1
	v_and_or_b32 v0, v0, s13, v5
	global_store_dword v[18:19], v0, off offset:512
	global_load_dword v0, v[16:17], off offset:3072
	s_nop 0
	global_load_dword v5, v[14:15], off offset:3072
	s_waitcnt vmcnt(22)
	v_xor_b32_e32 v22, 0x80000000, v23
	s_waitcnt vmcnt(21)
	v_bfe_u32 v23, v24, 16, 1
	v_add3_u32 v23, v24, v23, s1
	v_bfe_u32 v24, v22, 16, 1
	v_add3_u32 v22, v22, v24, s1
	global_load_dword v24, v[16:17], off offset:3328
	global_load_dword v38, v[14:15], off offset:3328
	v_lshrrev_b32_e32 v23, 16, v23
	v_and_or_b32 v22, v22, s13, v23
	global_store_dword v[18:19], v22, off offset:768
	s_waitcnt vmcnt(23)
	v_xor_b32_e32 v22, 0x80000000, v25
	s_waitcnt vmcnt(22)
	v_bfe_u32 v23, v26, 16, 1
	v_add3_u32 v23, v26, v23, s1
	global_load_dword v25, v[16:17], off offset:3584
	global_load_dword v26, v[14:15], off offset:3584
	v_bfe_u32 v39, v22, 16, 1
	v_lshrrev_b32_e32 v23, 16, v23
	v_add3_u32 v22, v22, v39, s1
	v_and_or_b32 v22, v22, s13, v23
	global_store_dword v[18:19], v22, off offset:1024
	global_load_dword v16, v[16:17], off offset:3840
	s_nop 0
	global_load_dword v14, v[14:15], off offset:3840
	s_waitcnt vmcnt(26)
	v_xor_b32_e32 v22, 0x80000000, v27
	s_waitcnt vmcnt(25)
	v_bfe_u32 v23, v28, 16, 1
	v_add3_u32 v15, v28, v23, s1
	v_bfe_u32 v17, v22, 16, 1
	v_lshrrev_b32_e32 v15, 16, v15
	v_add3_u32 v17, v22, v17, s1
	v_and_or_b32 v15, v17, s13, v15
	global_store_dword v[18:19], v15, off offset:1280
	s_waitcnt vmcnt(25)
	v_xor_b32_e32 v15, 0x80000000, v29
	s_waitcnt vmcnt(24)
	v_bfe_u32 v17, v30, 16, 1
	v_add3_u32 v17, v30, v17, s1
	v_bfe_u32 v22, v15, 16, 1
	v_lshrrev_b32_e32 v17, 16, v17
	v_add3_u32 v15, v15, v22, s1
	v_and_or_b32 v15, v15, s13, v17
	global_store_dword v[18:19], v15, off offset:1536
	s_waitcnt vmcnt(24)
	v_xor_b32_e32 v15, 0x80000000, v31
	s_waitcnt vmcnt(23)
	v_bfe_u32 v17, v32, 16, 1
	v_add3_u32 v17, v32, v17, s1
	v_bfe_u32 v22, v15, 16, 1
	v_lshrrev_b32_e32 v17, 16, v17
	v_add3_u32 v15, v15, v22, s1
	v_and_or_b32 v15, v15, s13, v17
	global_store_dword v[18:19], v15, off offset:1792
	s_waitcnt vmcnt(23)
	v_xor_b32_e32 v15, 0x80000000, v33
	s_waitcnt vmcnt(22)
	v_bfe_u32 v17, v34, 16, 1
	v_add3_u32 v17, v34, v17, s1
	v_bfe_u32 v22, v15, 16, 1
	v_lshrrev_b32_e32 v17, 16, v17
	v_add3_u32 v15, v15, v22, s1
	v_and_or_b32 v15, v15, s13, v17
	global_store_dword v[18:19], v15, off offset:2048
	s_waitcnt vmcnt(22)
	v_bfe_u32 v17, v3, 16, 1
	s_waitcnt vmcnt(21)
	v_xor_b32_e32 v15, 0x80000000, v35
	v_add3_u32 v3, v3, v17, s1
	v_bfe_u32 v17, v15, 16, 1
	v_lshrrev_b32_e32 v3, 16, v3
	v_add3_u32 v15, v15, v17, s1
	v_and_or_b32 v3, v15, s13, v3
	global_store_dword v[18:19], v3, off offset:2304
	s_waitcnt vmcnt(20)
	v_xor_b32_e32 v3, 0x80000000, v20
	s_waitcnt vmcnt(19)
	v_bfe_u32 v15, v36, 16, 1
	v_add3_u32 v15, v36, v15, s1
	v_bfe_u32 v17, v3, 16, 1
	v_lshrrev_b32_e32 v15, 16, v15
	v_add3_u32 v3, v3, v17, s1
	v_and_or_b32 v3, v3, s13, v15
	global_store_dword v[18:19], v3, off offset:2560
	s_waitcnt vmcnt(18)
	v_xor_b32_e32 v3, 0x80000000, v21
	s_waitcnt vmcnt(17)
	v_bfe_u32 v15, v37, 16, 1
	v_add3_u32 v15, v37, v15, s1
	v_bfe_u32 v17, v3, 16, 1
	v_lshrrev_b32_e32 v15, 16, v15
	v_add3_u32 v3, v3, v17, s1
	v_and_or_b32 v3, v3, s13, v15
	global_store_dword v[18:19], v3, off offset:2816
	s_waitcnt vmcnt(16)
	v_xor_b32_e32 v0, 0x80000000, v0
	s_waitcnt vmcnt(15)
	v_bfe_u32 v3, v5, 16, 1
	v_add3_u32 v3, v5, v3, s1
	v_bfe_u32 v5, v0, 16, 1
	v_lshrrev_b32_e32 v3, 16, v3
	v_add3_u32 v0, v0, v5, s1
	v_and_or_b32 v0, v0, s13, v3
	global_store_dword v[18:19], v0, off offset:3072
	s_waitcnt vmcnt(15)
	v_xor_b32_e32 v0, 0x80000000, v24
	s_waitcnt vmcnt(14)
	v_bfe_u32 v3, v38, 16, 1
	v_add3_u32 v3, v38, v3, s1
	v_bfe_u32 v5, v0, 16, 1
	v_lshrrev_b32_e32 v3, 16, v3
	v_add3_u32 v0, v0, v5, s1
	v_and_or_b32 v0, v0, s13, v3
	global_store_dword v[18:19], v0, off offset:3328
	s_waitcnt vmcnt(13)
	v_xor_b32_e32 v0, 0x80000000, v25
	s_waitcnt vmcnt(12)
	v_bfe_u32 v3, v26, 16, 1
	v_add3_u32 v3, v26, v3, s1
	v_bfe_u32 v5, v0, 16, 1
	v_lshrrev_b32_e32 v3, 16, v3
	v_add3_u32 v0, v0, v5, s1
	v_and_or_b32 v0, v0, s13, v3
	global_store_dword v[18:19], v0, off offset:3584
	s_waitcnt vmcnt(11)
	v_xor_b32_e32 v0, 0x80000000, v16
	s_waitcnt vmcnt(10)
	v_bfe_u32 v3, v14, 16, 1
	v_add3_u32 v3, v14, v3, s1
	v_bfe_u32 v5, v0, 16, 1
	v_lshrrev_b32_e32 v3, 16, v3
	v_add3_u32 v0, v0, v5, s1
	v_and_or_b32 v0, v0, s13, v3
	global_store_dword v[18:19], v0, off offset:3840
	s_cbranch_scc0 .LBB0_68
